# K-loops: fragment reads ordered by first use, counted lgkmcnt per MFMA, no lgkmcnt(8) before the phase barrier
# baseline (speedup 1.0000x reference)
.LBB0_119:
	s_add_u32 s26, s6, 0xfff80080
	s_addc_u32 s27, s7, -1
	s_add_i32 s66, 0, 0x10000
	v_add_u32_e32 v44, s66, v194
	ds_read_b128 v[24:27], v44
	ds_read_b128 v[40:43], v44 offset:2048
	ds_read_b128 v[32:35], v44 offset:1024
	ds_read_b128 v[44:47], v44 offset:3072
	s_cmp_eq_u32 s57, 28
	s_cselect_b32 s29, s25, s27
	s_cselect_b32 s28, s24, s26
	s_cselect_b32 s27, s9, s19
	s_cselect_b32 s26, s8, s11
	v_lshl_add_u64 v[180:181], s[6:7], 0, v[168:169]
	s_add_i32 m0, s36, 0xc000
	ds_read_b128 v[172:175], v196
	ds_read_b128 v[198:201], v196 offset:2048
	ds_read_b128 v[206:209], v196 offset:4096
	ds_read_b128 v[214:217], v196 offset:6144
	ds_read_b128 v[176:179], v196 offset:1024
	ds_read_b128 v[202:205], v196 offset:3072
	ds_read_b128 v[210:213], v196 offset:5120
	ds_read_b128 v[218:221], v196 offset:7168
	global_load_lds_dwordx4 v[180:181], off
	v_lshl_add_u64 v[180:181], s[6:7], 0, v[170:171]
	s_add_i32 m0, s36, 0xe000
	s_nop 0
	global_load_lds_dwordx4 v[180:181], off
	s_barrier
	s_setprio 1
	s_waitcnt lgkmcnt(7)
	v_mfma_f32_16x16x32_bf16 v[140:143], v[24:27], v[172:175], v[140:143]
	v_mfma_f32_16x16x32_bf16 v[136:139], v[40:43], v[172:175], v[136:139]
	s_waitcnt lgkmcnt(6)
	v_mfma_f32_16x16x32_bf16 v[124:127], v[24:27], v[198:201], v[124:127]
	v_mfma_f32_16x16x32_bf16 v[120:123], v[40:43], v[198:201], v[120:123]
	s_waitcnt lgkmcnt(5)
	v_mfma_f32_16x16x32_bf16 v[108:111], v[24:27], v[206:209], v[108:111]
	v_mfma_f32_16x16x32_bf16 v[104:107], v[40:43], v[206:209], v[104:107]
	s_waitcnt lgkmcnt(4)
	v_mfma_f32_16x16x32_bf16 v[92:95], v[24:27], v[214:217], v[92:95]
	v_mfma_f32_16x16x32_bf16 v[88:91], v[40:43], v[214:217], v[88:91]
	s_waitcnt lgkmcnt(3)
	v_mfma_f32_16x16x32_bf16 v[140:143], v[32:35], v[176:179], v[140:143]
	v_mfma_f32_16x16x32_bf16 v[136:139], v[44:47], v[176:179], v[136:139]
	s_waitcnt lgkmcnt(2)
	v_mfma_f32_16x16x32_bf16 v[124:127], v[32:35], v[202:205], v[124:127]
	v_mfma_f32_16x16x32_bf16 v[120:123], v[44:47], v[202:205], v[120:123]
	s_waitcnt lgkmcnt(1)
	v_mfma_f32_16x16x32_bf16 v[108:111], v[32:35], v[210:213], v[108:111]
	v_mfma_f32_16x16x32_bf16 v[104:107], v[44:47], v[210:213], v[104:107]
	s_waitcnt lgkmcnt(0)
	v_mfma_f32_16x16x32_bf16 v[92:95], v[32:35], v[218:221], v[92:95]
	v_mfma_f32_16x16x32_bf16 v[88:91], v[44:47], v[218:221], v[88:91]
	s_setprio 0
	s_barrier
	s_add_i32 s70, 0, 0x14000
	v_add_u32_e32 v180, s70, v194
	s_add_i32 s66, s66, s35
	ds_read_b128 v[222:225], v180
	ds_read_b128 v[230:233], v180 offset:2048
	ds_read_b128 v[226:229], v180 offset:1024
	ds_read_b128 v[234:237], v180 offset:3072
	v_lshl_add_u64 v[180:181], s[26:27], 0, v[144:145]
	s_mov_b32 m0, s66
	v_lshl_add_u64 v[238:239], s[26:27], 0, v[166:167]
	global_load_lds_dwordx4 v[180:181], off
	s_add_i32 m0, s66, 0x2000
	s_nop 0
	global_load_lds_dwordx4 v[238:239], off
	s_barrier
	s_setprio 1
	s_waitcnt lgkmcnt(3)
	v_mfma_f32_16x16x32_bf16 v[132:135], v[222:225], v[172:175], v[132:135]
	s_waitcnt lgkmcnt(2)
	v_mfma_f32_16x16x32_bf16 v[128:131], v[230:233], v[172:175], v[128:131]
	v_mfma_f32_16x16x32_bf16 v[116:119], v[222:225], v[198:201], v[116:119]
	v_mfma_f32_16x16x32_bf16 v[112:115], v[230:233], v[198:201], v[112:115]
	v_mfma_f32_16x16x32_bf16 v[100:103], v[222:225], v[206:209], v[100:103]
	v_mfma_f32_16x16x32_bf16 v[96:99], v[230:233], v[206:209], v[96:99]
	v_mfma_f32_16x16x32_bf16 v[84:87], v[222:225], v[214:217], v[84:87]
	v_mfma_f32_16x16x32_bf16 v[80:83], v[230:233], v[214:217], v[80:83]
	s_waitcnt lgkmcnt(1)
	v_mfma_f32_16x16x32_bf16 v[132:135], v[226:229], v[176:179], v[132:135]
	s_waitcnt lgkmcnt(0)
	v_mfma_f32_16x16x32_bf16 v[128:131], v[234:237], v[176:179], v[128:131]
	v_mfma_f32_16x16x32_bf16 v[116:119], v[226:229], v[202:205], v[116:119]
	v_mfma_f32_16x16x32_bf16 v[112:115], v[234:237], v[202:205], v[112:115]
	v_mfma_f32_16x16x32_bf16 v[100:103], v[226:229], v[210:213], v[100:103]
	v_mfma_f32_16x16x32_bf16 v[96:99], v[234:237], v[210:213], v[96:99]
	v_mfma_f32_16x16x32_bf16 v[84:87], v[226:229], v[218:221], v[84:87]
	v_mfma_f32_16x16x32_bf16 v[80:83], v[234:237], v[218:221], v[80:83]
	s_setprio 0
	s_mov_b32 m0, s36
	v_lshl_add_u64 v[240:241], s[28:29], 0, v[162:163]
	s_barrier
	ds_read_b128 v[172:175], v196 offset:16384
	ds_read_b128 v[198:201], v196 offset:18432
	ds_read_b128 v[206:209], v196 offset:20480
	ds_read_b128 v[214:217], v196 offset:22528
	ds_read_b128 v[176:179], v196 offset:17408
	ds_read_b128 v[202:205], v196 offset:19456
	ds_read_b128 v[210:213], v196 offset:21504
	ds_read_b128 v[218:221], v196 offset:23552
	global_load_lds_dwordx4 v[240:241], off
	v_lshl_add_u64 v[242:243], s[28:29], 0, v[164:165]
	s_mov_b32 m0, s37
	s_nop 0
	global_load_lds_dwordx4 v[242:243], off
	s_barrier
	s_setprio 1
	s_waitcnt lgkmcnt(7)
	v_mfma_f32_16x16x32_bf16 v[76:79], v[24:27], v[172:175], v[76:79]
	v_mfma_f32_16x16x32_bf16 v[72:75], v[40:43], v[172:175], v[72:75]
	s_waitcnt lgkmcnt(6)
	v_mfma_f32_16x16x32_bf16 v[60:63], v[24:27], v[198:201], v[60:63]
	v_mfma_f32_16x16x32_bf16 v[56:59], v[40:43], v[198:201], v[56:59]
	s_waitcnt lgkmcnt(5)
	v_mfma_f32_16x16x32_bf16 v[36:39], v[24:27], v[206:209], v[36:39]
	v_mfma_f32_16x16x32_bf16 v[28:31], v[40:43], v[206:209], v[28:31]
	s_waitcnt lgkmcnt(4)
	v_mfma_f32_16x16x32_bf16 v[12:15], v[24:27], v[214:217], v[12:15]
	v_mfma_f32_16x16x32_bf16 v[8:11], v[40:43], v[214:217], v[8:11]
	s_waitcnt lgkmcnt(3)
	v_mfma_f32_16x16x32_bf16 v[76:79], v[32:35], v[176:179], v[76:79]
	v_mfma_f32_16x16x32_bf16 v[72:75], v[44:47], v[176:179], v[72:75]
	s_waitcnt lgkmcnt(2)
	v_mfma_f32_16x16x32_bf16 v[60:63], v[32:35], v[202:205], v[60:63]
	v_mfma_f32_16x16x32_bf16 v[56:59], v[44:47], v[202:205], v[56:59]
	s_waitcnt lgkmcnt(1)
	v_mfma_f32_16x16x32_bf16 v[36:39], v[32:35], v[210:213], v[36:39]
	v_mfma_f32_16x16x32_bf16 v[28:31], v[44:47], v[210:213], v[28:31]
	s_waitcnt lgkmcnt(0)
	v_mfma_f32_16x16x32_bf16 v[12:15], v[32:35], v[218:221], v[12:15]
	v_mfma_f32_16x16x32_bf16 v[8:11], v[44:47], v[218:221], v[8:11]
	s_setprio 0
	s_barrier
	s_add_u32 s66, s26, 0x80000
	s_addc_u32 s67, s27, 0
	s_add_i32 s70, s70, s35
	v_lshl_add_u64 v[24:25], s[66:67], 0, v[144:145]
	s_mov_b32 m0, s70
	s_nop 0
	global_load_lds_dwordx4 v[24:25], off
	v_lshl_add_u64 v[24:25], s[66:67], 0, v[166:167]
	s_add_i32 m0, s70, 0x2000
	s_nop 0
	global_load_lds_dwordx4 v[24:25], off
	s_waitcnt vmcnt(6)
	s_barrier
	s_setprio 1
	v_mfma_f32_16x16x32_bf16 v[20:23], v[222:225], v[206:209], v[20:23]
	v_mfma_f32_16x16x32_bf16 v[16:19], v[230:233], v[206:209], v[16:19]
	v_mfma_f32_16x16x32_bf16 v[4:7], v[222:225], v[214:217], v[4:7]
	v_mfma_f32_16x16x32_bf16 v[0:3], v[230:233], v[214:217], v[0:3]
	v_mfma_f32_16x16x32_bf16 v[24:27], v[222:225], v[172:175], v[68:71]
	v_mfma_f32_16x16x32_bf16 v[32:35], v[230:233], v[172:175], v[64:67]
	v_mfma_f32_16x16x32_bf16 v[40:43], v[222:225], v[198:201], v[52:55]
	v_mfma_f32_16x16x32_bf16 v[44:47], v[230:233], v[198:201], v[48:51]
	v_mfma_f32_16x16x32_bf16 v[20:23], v[226:229], v[210:213], v[20:23]
	v_mfma_f32_16x16x32_bf16 v[16:19], v[234:237], v[210:213], v[16:19]
	v_mfma_f32_16x16x32_bf16 v[4:7], v[226:229], v[218:221], v[4:7]
	v_mfma_f32_16x16x32_bf16 v[0:3], v[234:237], v[218:221], v[0:3]
	v_mfma_f32_16x16x32_bf16 v[24:27], v[226:229], v[176:179], v[24:27]
	v_mfma_f32_16x16x32_bf16 v[32:35], v[234:237], v[176:179], v[32:35]
	v_mfma_f32_16x16x32_bf16 v[40:43], v[226:229], v[202:205], v[40:43]
	v_mfma_f32_16x16x32_bf16 v[44:47], v[234:237], v[202:205], v[44:47]
	s_setprio 0
	s_add_i32 s66, 0, 0x18000
	v_add_u32_e32 v68, s66, v194
	s_barrier
	ds_read_b128 v[48:51], v68
	ds_read_b128 v[64:67], v68 offset:2048
	ds_read_b128 v[52:55], v68 offset:1024
	ds_read_b128 v[68:71], v68 offset:3072
	s_add_u32 s28, s28, 0x80000
	s_addc_u32 s29, s29, 0
	s_mov_b32 m0, s50
	v_lshl_add_u64 v[222:223], s[28:29], 0, v[162:163]
	ds_read_b128 v[172:175], v196 offset:32768
	ds_read_b128 v[198:201], v196 offset:34816
	ds_read_b128 v[206:209], v196 offset:36864
	ds_read_b128 v[214:217], v196 offset:38912
	ds_read_b128 v[176:179], v196 offset:33792
	ds_read_b128 v[202:205], v196 offset:35840
	ds_read_b128 v[210:213], v196 offset:37888
	ds_read_b128 v[218:221], v196 offset:39936
	global_load_lds_dwordx4 v[222:223], off
	v_lshl_add_u64 v[222:223], s[28:29], 0, v[164:165]
	s_mov_b32 m0, s51
	s_nop 0
	global_load_lds_dwordx4 v[222:223], off
	s_barrier
	s_setprio 1
	s_waitcnt lgkmcnt(7)
	v_mfma_f32_16x16x32_bf16 v[140:143], v[48:51], v[172:175], v[140:143]
	v_mfma_f32_16x16x32_bf16 v[136:139], v[64:67], v[172:175], v[136:139]
	s_waitcnt lgkmcnt(6)
	v_mfma_f32_16x16x32_bf16 v[124:127], v[48:51], v[198:201], v[124:127]
	v_mfma_f32_16x16x32_bf16 v[120:123], v[64:67], v[198:201], v[120:123]
	s_waitcnt lgkmcnt(5)
	v_mfma_f32_16x16x32_bf16 v[108:111], v[48:51], v[206:209], v[108:111]
	v_mfma_f32_16x16x32_bf16 v[104:107], v[64:67], v[206:209], v[104:107]
	s_waitcnt lgkmcnt(4)
	v_mfma_f32_16x16x32_bf16 v[92:95], v[48:51], v[214:217], v[92:95]
	v_mfma_f32_16x16x32_bf16 v[88:91], v[64:67], v[214:217], v[88:91]
	s_waitcnt lgkmcnt(3)
	v_mfma_f32_16x16x32_bf16 v[140:143], v[52:55], v[176:179], v[140:143]
	v_mfma_f32_16x16x32_bf16 v[136:139], v[68:71], v[176:179], v[136:139]
	s_waitcnt lgkmcnt(2)
	v_mfma_f32_16x16x32_bf16 v[124:127], v[52:55], v[202:205], v[124:127]
	v_mfma_f32_16x16x32_bf16 v[120:123], v[68:71], v[202:205], v[120:123]
	s_waitcnt lgkmcnt(1)
	v_mfma_f32_16x16x32_bf16 v[108:111], v[52:55], v[210:213], v[108:111]
	v_mfma_f32_16x16x32_bf16 v[104:107], v[68:71], v[210:213], v[104:107]
	s_waitcnt lgkmcnt(0)
	v_mfma_f32_16x16x32_bf16 v[92:95], v[52:55], v[218:221], v[92:95]
	v_mfma_f32_16x16x32_bf16 v[88:91], v[68:71], v[218:221], v[88:91]
	s_setprio 0
	s_barrier
	s_add_i32 s28, 0, 0x1c000
	s_add_i32 s29, s66, s35
	v_add_u32_e32 v197, s28, v194
	v_lshl_add_u64 v[180:181], v[180:181], 0, s[86:87]
	s_mov_b32 m0, s29
	ds_read_b128 v[222:225], v197
	ds_read_b128 v[230:233], v197 offset:2048
	ds_read_b128 v[226:229], v197 offset:1024
	ds_read_b128 v[234:237], v197 offset:3072
	global_load_lds_dwordx4 v[180:181], off
	v_lshl_add_u64 v[180:181], v[238:239], 0, s[86:87]
	s_add_i32 m0, s29, 0x2000
	s_nop 0
	global_load_lds_dwordx4 v[180:181], off
	s_barrier
	s_setprio 1
	s_waitcnt lgkmcnt(3)
	v_mfma_f32_16x16x32_bf16 v[132:135], v[222:225], v[172:175], v[132:135]
	s_waitcnt lgkmcnt(2)
	v_mfma_f32_16x16x32_bf16 v[128:131], v[230:233], v[172:175], v[128:131]
	v_mfma_f32_16x16x32_bf16 v[116:119], v[222:225], v[198:201], v[116:119]
	v_mfma_f32_16x16x32_bf16 v[112:115], v[230:233], v[198:201], v[112:115]
	v_mfma_f32_16x16x32_bf16 v[100:103], v[222:225], v[206:209], v[100:103]
	v_mfma_f32_16x16x32_bf16 v[96:99], v[230:233], v[206:209], v[96:99]
	v_mfma_f32_16x16x32_bf16 v[84:87], v[222:225], v[214:217], v[84:87]
	v_mfma_f32_16x16x32_bf16 v[80:83], v[230:233], v[214:217], v[80:83]
	s_waitcnt lgkmcnt(1)
	v_mfma_f32_16x16x32_bf16 v[132:135], v[226:229], v[176:179], v[132:135]
	s_waitcnt lgkmcnt(0)
	v_mfma_f32_16x16x32_bf16 v[128:131], v[234:237], v[176:179], v[128:131]
	v_mfma_f32_16x16x32_bf16 v[116:119], v[226:229], v[202:205], v[116:119]
	v_mfma_f32_16x16x32_bf16 v[112:115], v[234:237], v[202:205], v[112:115]
	v_mfma_f32_16x16x32_bf16 v[100:103], v[226:229], v[210:213], v[100:103]
	v_mfma_f32_16x16x32_bf16 v[96:99], v[234:237], v[210:213], v[96:99]
	v_mfma_f32_16x16x32_bf16 v[84:87], v[226:229], v[218:221], v[84:87]
	v_mfma_f32_16x16x32_bf16 v[80:83], v[234:237], v[218:221], v[80:83]
	s_setprio 0
	s_mov_b32 m0, s52
	v_lshl_add_u64 v[180:181], v[240:241], 0, s[86:87]
	s_barrier
	ds_read_b128 v[172:175], v196 offset:49152
	ds_read_b128 v[198:201], v196 offset:51200
	ds_read_b128 v[206:209], v196 offset:53248
	ds_read_b128 v[214:217], v196 offset:55296
	ds_read_b128 v[176:179], v196 offset:50176
	ds_read_b128 v[202:205], v196 offset:52224
	ds_read_b128 v[210:213], v196 offset:54272
	ds_read_b128 v[218:221], v196 offset:56320
	global_load_lds_dwordx4 v[180:181], off
	v_lshl_add_u64 v[180:181], v[242:243], 0, s[86:87]
	s_mov_b32 m0, s53
	s_nop 0
	global_load_lds_dwordx4 v[180:181], off
	s_barrier
	s_setprio 1
	s_waitcnt lgkmcnt(7)
	v_mfma_f32_16x16x32_bf16 v[76:79], v[48:51], v[172:175], v[76:79]
	v_mfma_f32_16x16x32_bf16 v[72:75], v[64:67], v[172:175], v[72:75]
	s_waitcnt lgkmcnt(6)
	v_mfma_f32_16x16x32_bf16 v[60:63], v[48:51], v[198:201], v[60:63]
	v_mfma_f32_16x16x32_bf16 v[56:59], v[64:67], v[198:201], v[56:59]
	s_waitcnt lgkmcnt(5)
	v_mfma_f32_16x16x32_bf16 v[36:39], v[48:51], v[206:209], v[36:39]
	v_mfma_f32_16x16x32_bf16 v[28:31], v[64:67], v[206:209], v[28:31]
	s_waitcnt lgkmcnt(4)
	v_mfma_f32_16x16x32_bf16 v[12:15], v[48:51], v[214:217], v[12:15]
	v_mfma_f32_16x16x32_bf16 v[8:11], v[64:67], v[214:217], v[8:11]
	s_waitcnt lgkmcnt(3)
	v_mfma_f32_16x16x32_bf16 v[76:79], v[52:55], v[176:179], v[76:79]
	v_mfma_f32_16x16x32_bf16 v[72:75], v[68:71], v[176:179], v[72:75]
	s_waitcnt lgkmcnt(2)
	v_mfma_f32_16x16x32_bf16 v[60:63], v[52:55], v[202:205], v[60:63]
	v_mfma_f32_16x16x32_bf16 v[56:59], v[68:71], v[202:205], v[56:59]
	s_waitcnt lgkmcnt(1)
	v_mfma_f32_16x16x32_bf16 v[36:39], v[52:55], v[210:213], v[36:39]
	v_mfma_f32_16x16x32_bf16 v[28:31], v[68:71], v[210:213], v[28:31]
	s_waitcnt lgkmcnt(0)
	v_mfma_f32_16x16x32_bf16 v[12:15], v[52:55], v[218:221], v[12:15]
	v_mfma_f32_16x16x32_bf16 v[8:11], v[68:71], v[218:221], v[8:11]
	s_setprio 0
	s_barrier
	s_add_u32 s26, s26, 0x80080
	s_addc_u32 s27, s27, 0
	s_add_i32 s28, s28, s35
	v_lshl_add_u64 v[48:49], s[26:27], 0, v[144:145]
	s_mov_b32 m0, s28
	s_nop 0
	global_load_lds_dwordx4 v[48:49], off
	v_lshl_add_u64 v[48:49], s[26:27], 0, v[166:167]
	s_add_i32 m0, s28, 0x2000
	s_nop 0
	global_load_lds_dwordx4 v[48:49], off
	s_waitcnt vmcnt(6)
	s_barrier
	s_setprio 1
	v_mfma_f32_16x16x32_bf16 v[24:27], v[222:225], v[172:175], v[24:27]
	v_mfma_f32_16x16x32_bf16 v[68:71], v[226:229], v[176:179], v[24:27]
	v_mfma_f32_16x16x32_bf16 v[24:27], v[230:233], v[172:175], v[32:35]
	v_mfma_f32_16x16x32_bf16 v[64:67], v[234:237], v[176:179], v[24:27]
	v_mfma_f32_16x16x32_bf16 v[24:27], v[222:225], v[198:201], v[40:43]
	v_mfma_f32_16x16x32_bf16 v[52:55], v[226:229], v[202:205], v[24:27]
	v_mfma_f32_16x16x32_bf16 v[24:27], v[230:233], v[198:201], v[44:47]
	v_mfma_f32_16x16x32_bf16 v[20:23], v[222:225], v[206:209], v[20:23]
	v_mfma_f32_16x16x32_bf16 v[16:19], v[230:233], v[206:209], v[16:19]
	v_mfma_f32_16x16x32_bf16 v[4:7], v[222:225], v[214:217], v[4:7]
	v_mfma_f32_16x16x32_bf16 v[0:3], v[230:233], v[214:217], v[0:3]
	v_mfma_f32_16x16x32_bf16 v[48:51], v[234:237], v[202:205], v[24:27]
	v_mfma_f32_16x16x32_bf16 v[20:23], v[226:229], v[210:213], v[20:23]
	v_mfma_f32_16x16x32_bf16 v[16:19], v[234:237], v[210:213], v[16:19]
	v_mfma_f32_16x16x32_bf16 v[4:7], v[226:229], v[218:221], v[4:7]
	v_mfma_f32_16x16x32_bf16 v[0:3], v[234:237], v[218:221], v[0:3]
	s_setprio 0
	s_add_i32 s57, s57, 2
	s_add_u32 s6, s6, 0x100
	s_addc_u32 s7, s7, 0
	s_add_u32 s11, s11, 0x100
	s_addc_u32 s19, s19, 0
	s_cmp_gt_u32 s57, 29
	s_barrier
	s_cbranch_scc0 .LBB0_119
	s_load_dwordx2 s[6:7], s[20:21], 0x58
	v_lshl_or_b32 v172, s56, 8, v195
	v_ashrrev_i32_e32 v173, 31, v172
	s_cmp_gt_i32 s56, 7
	v_lshl_add_u32 v174, s10, 8, v193
	s_waitcnt lgkmcnt(0)
	v_lshl_add_u64 v[32:33], v[172:173], 2, s[6:7]
	global_load_dwordx4 v[40:43], v[32:33], off offset:16
	global_load_dwordx4 v[44:47], v[32:33], off
	global_load_dwordx4 v[24:27], v[32:33], off offset:528
	s_nop 0
	global_load_dwordx4 v[32:35], v[32:33], off offset:512
	s_cselect_b64 s[10:11], -1, 0
	s_lshl_b32 s6, s56, 2
	s_sub_i32 s6, s6, 32
	s_ashr_i32 s7, s6, 31
	s_or_b64 s[26:27], s[6:7], s[76:77]
	s_mov_b32 s6, 0x3e6d3388
	s_mov_b32 s28, 0xbf3a00e3
	v_ashrrev_i32_e32 v175, 31, v174
	v_lshlrev_b64 v[176:177], 13, v[174:175]
	v_lshl_add_u64 v[176:177], s[14:15], 0, v[176:177]
	v_lshl_add_u64 v[176:177], v[172:173], 1, v[176:177]
	s_cmp_lt_i32 s56, 8
	s_waitcnt vmcnt(0)
	v_pk_add_f32 v[136:137], v[136:137], v[40:41]
	v_pk_add_f32 v[140:141], v[140:141], v[44:45]
	v_pk_add_f32 v[142:143], v[142:143], v[46:47]
	v_and_b32_e32 v181, 0x7fffffff, v141
	v_and_b32_e32 v180, 0x7fffffff, v140
	v_pk_fma_f32 v[178:179], v[180:181], s[6:7], 1.0 op_sel_hi:[1,0,0]
	v_pk_mul_f32 v[202:203], v[140:141], v[140:141]
	v_rcp_f32_e32 v198, v178
	v_rcp_f32_e32 v199, v179
	v_mov_b64_e32 v[178:179], s[28:29]
	v_pk_mul_f32 v[202:203], v[202:203], s[60:61] op_sel_hi:[1,0]
	v_pk_add_f32 v[138:139], v[138:139], v[42:43]
	v_pk_fma_f32 v[200:201], v[198:199], s[92:93], v[178:179] op_sel_hi:[1,0,0]
	v_exp_f32_e32 v202, v202
	v_pk_fma_f32 v[200:201], v[198:199], v[200:201], s[96:97] op_sel_hi:[1,1,0]
	v_exp_f32_e32 v203, v203
	v_pk_fma_f32 v[200:201], v[198:199], v[200:201], s[44:45] op_sel_hi:[1,1,0]
	v_pk_add_f32 v[132:133], v[132:133], v[32:33]
	v_pk_fma_f32 v[200:201], v[198:199], v[200:201], s[58:59] op_sel_hi:[1,1,0]
	v_pk_add_f32 v[134:135], v[134:135], v[34:35]
	v_pk_mul_f32 v[198:199], v[198:199], v[200:201]
	v_pk_mul_f32 v[200:201], v[142:143], v[142:143]
	v_pk_fma_f32 v[198:199], v[202:203], v[198:199], 0.5 op_sel_hi:[1,1,0] neg_lo:[1,0,0] neg_hi:[1,0,0]
	v_pk_mul_f32 v[200:201], v[200:201], s[60:61] op_sel_hi:[1,0]
	v_pk_mul_f32 v[180:181], v[180:181], v[198:199]
	v_exp_f32_e32 v200, v200
	v_pk_fma_f32 v[140:141], v[140:141], 0.5, v[180:181] op_sel_hi:[1,0,1]
	v_and_b32_e32 v181, 0x7fffffff, v143
	v_and_b32_e32 v180, 0x7fffffff, v142
	v_pk_fma_f32 v[198:199], v[180:181], s[6:7], 1.0 op_sel_hi:[1,0,0]
	v_exp_f32_e32 v201, v201
	v_rcp_f32_e32 v198, v198
	v_rcp_f32_e32 v199, v199
	v_pk_add_f32 v[128:129], v[128:129], v[24:25]
	v_pk_add_f32 v[130:131], v[130:131], v[26:27]
	v_pk_fma_f32 v[202:203], v[198:199], s[92:93], v[178:179] op_sel_hi:[1,0,0]
	s_nop 0
	v_pk_fma_f32 v[202:203], v[198:199], v[202:203], s[96:97] op_sel_hi:[1,1,0]
	s_nop 0
	v_pk_fma_f32 v[202:203], v[198:199], v[202:203], s[44:45] op_sel_hi:[1,1,0]
	s_nop 0
	v_pk_fma_f32 v[202:203], v[198:199], v[202:203], s[58:59] op_sel_hi:[1,1,0]
	s_nop 0
	v_pk_mul_f32 v[198:199], v[198:199], v[202:203]
	v_pk_mul_f32 v[202:203], v[136:137], v[136:137]
	v_pk_fma_f32 v[198:199], v[200:201], v[198:199], 0.5 op_sel_hi:[1,1,0] neg_lo:[1,0,0] neg_hi:[1,0,0]
	v_pk_mul_f32 v[202:203], v[202:203], s[60:61] op_sel_hi:[1,0]
	v_pk_mul_f32 v[180:181], v[180:181], v[198:199]
	v_exp_f32_e32 v202, v202
	v_pk_fma_f32 v[142:143], v[142:143], 0.5, v[180:181] op_sel_hi:[1,0,1]
	v_and_b32_e32 v181, 0x7fffffff, v137
	v_and_b32_e32 v180, 0x7fffffff, v136
	v_pk_fma_f32 v[198:199], v[180:181], s[6:7], 1.0 op_sel_hi:[1,0,0]
	v_exp_f32_e32 v203, v203
	v_rcp_f32_e32 v198, v198
	v_rcp_f32_e32 v199, v199
	s_nop 0
	v_pk_fma_f32 v[200:201], v[198:199], s[92:93], v[178:179] op_sel_hi:[1,0,0]
	s_nop 0
	v_pk_fma_f32 v[200:201], v[198:199], v[200:201], s[96:97] op_sel_hi:[1,1,0]
	s_nop 0
	v_pk_fma_f32 v[200:201], v[198:199], v[200:201], s[44:45] op_sel_hi:[1,1,0]
	s_nop 0
	v_pk_fma_f32 v[200:201], v[198:199], v[200:201], s[58:59] op_sel_hi:[1,1,0]
	s_nop 0
	v_pk_mul_f32 v[198:199], v[198:199], v[200:201]
	v_pk_mul_f32 v[200:201], v[138:139], v[138:139]
	v_pk_fma_f32 v[198:199], v[202:203], v[198:199], 0.5 op_sel_hi:[1,1,0] neg_lo:[1,0,0] neg_hi:[1,0,0]
	v_pk_mul_f32 v[200:201], v[200:201], s[60:61] op_sel_hi:[1,0]
	v_pk_mul_f32 v[180:181], v[180:181], v[198:199]
	v_exp_f32_e32 v200, v200
	v_pk_fma_f32 v[136:137], v[136:137], 0.5, v[180:181] op_sel_hi:[1,0,1]
	v_and_b32_e32 v181, 0x7fffffff, v139
	v_and_b32_e32 v180, 0x7fffffff, v138
	v_pk_fma_f32 v[198:199], v[180:181], s[6:7], 1.0 op_sel_hi:[1,0,0]
	v_exp_f32_e32 v201, v201
	v_rcp_f32_e32 v198, v198
	v_rcp_f32_e32 v199, v199
	s_nop 0
	v_pk_fma_f32 v[202:203], v[198:199], s[92:93], v[178:179] op_sel_hi:[1,0,0]
	s_nop 0
	v_pk_fma_f32 v[202:203], v[198:199], v[202:203], s[96:97] op_sel_hi:[1,1,0]
	s_nop 0
	v_pk_fma_f32 v[202:203], v[198:199], v[202:203], s[44:45] op_sel_hi:[1,1,0]
	s_nop 0
	v_pk_fma_f32 v[202:203], v[198:199], v[202:203], s[58:59] op_sel_hi:[1,1,0]
	s_nop 0
	v_pk_mul_f32 v[198:199], v[198:199], v[202:203]
	v_pk_mul_f32 v[202:203], v[132:133], v[132:133]
	v_pk_fma_f32 v[198:199], v[200:201], v[198:199], 0.5 op_sel_hi:[1,1,0] neg_lo:[1,0,0] neg_hi:[1,0,0]
	v_cvt_pk_bf16_f32 v200, v136, v137
	v_pk_mul_f32 v[202:203], v[202:203], s[60:61] op_sel_hi:[1,0]
	v_pk_mul_f32 v[180:181], v[180:181], v[198:199]
	v_cvt_pk_bf16_f32 v198, v140, v141
	v_cvt_pk_bf16_f32 v199, v142, v143
	v_exp_f32_e32 v202, v202
	v_pk_fma_f32 v[138:139], v[138:139], 0.5, v[180:181] op_sel_hi:[1,0,1]
	v_and_b32_e32 v181, 0x7fffffff, v133
	v_and_b32_e32 v180, 0x7fffffff, v132
	v_cvt_pk_bf16_f32 v201, v138, v139
	global_store_dwordx4 v[176:177], v[198:201], off
	v_exp_f32_e32 v203, v203
	s_nop 0
	v_pk_fma_f32 v[198:199], v[180:181], s[6:7], 1.0 op_sel_hi:[1,0,0]
	s_nop 0
	v_rcp_f32_e32 v198, v198
	v_rcp_f32_e32 v199, v199
	s_nop 0
	v_pk_fma_f32 v[200:201], v[198:199], s[92:93], v[178:179] op_sel_hi:[1,0,0]
	s_nop 0
	v_pk_fma_f32 v[200:201], v[198:199], v[200:201], s[96:97] op_sel_hi:[1,1,0]
	s_nop 0
	v_pk_fma_f32 v[200:201], v[198:199], v[200:201], s[44:45] op_sel_hi:[1,1,0]
	s_nop 0
	v_pk_fma_f32 v[200:201], v[198:199], v[200:201], s[58:59] op_sel_hi:[1,1,0]
	s_nop 0
	v_pk_mul_f32 v[198:199], v[198:199], v[200:201]
	v_pk_mul_f32 v[200:201], v[134:135], v[134:135]
	v_pk_fma_f32 v[198:199], v[202:203], v[198:199], 0.5 op_sel_hi:[1,1,0] neg_lo:[1,0,0] neg_hi:[1,0,0]
	v_pk_mul_f32 v[200:201], v[200:201], s[60:61] op_sel_hi:[1,0]
	v_pk_mul_f32 v[180:181], v[180:181], v[198:199]
	v_exp_f32_e32 v200, v200
	v_pk_fma_f32 v[132:133], v[132:133], 0.5, v[180:181] op_sel_hi:[1,0,1]
	v_and_b32_e32 v181, 0x7fffffff, v135
	v_and_b32_e32 v180, 0x7fffffff, v134
	v_pk_fma_f32 v[198:199], v[180:181], s[6:7], 1.0 op_sel_hi:[1,0,0]
	v_exp_f32_e32 v201, v201
	v_rcp_f32_e32 v198, v198
	v_rcp_f32_e32 v199, v199
	s_nop 0
	v_pk_fma_f32 v[202:203], v[198:199], s[92:93], v[178:179] op_sel_hi:[1,0,0]
	s_nop 0
	v_pk_fma_f32 v[202:203], v[198:199], v[202:203], s[96:97] op_sel_hi:[1,1,0]
	s_nop 0
	v_pk_fma_f32 v[202:203], v[198:199], v[202:203], s[44:45] op_sel_hi:[1,1,0]
	s_nop 0
	v_pk_fma_f32 v[202:203], v[198:199], v[202:203], s[58:59] op_sel_hi:[1,1,0]
	s_nop 0
	v_pk_mul_f32 v[198:199], v[198:199], v[202:203]
	v_pk_mul_f32 v[202:203], v[128:129], v[128:129]
	v_pk_fma_f32 v[198:199], v[200:201], v[198:199], 0.5 op_sel_hi:[1,1,0] neg_lo:[1,0,0] neg_hi:[1,0,0]
	v_pk_mul_f32 v[202:203], v[202:203], s[60:61] op_sel_hi:[1,0]
	v_pk_mul_f32 v[180:181], v[180:181], v[198:199]
	v_exp_f32_e32 v202, v202
	v_pk_fma_f32 v[134:135], v[134:135], 0.5, v[180:181] op_sel_hi:[1,0,1]
	v_and_b32_e32 v181, 0x7fffffff, v129
	v_and_b32_e32 v180, 0x7fffffff, v128
	v_pk_fma_f32 v[198:199], v[180:181], s[6:7], 1.0 op_sel_hi:[1,0,0]
	v_exp_f32_e32 v203, v203
	v_rcp_f32_e32 v198, v198
	v_rcp_f32_e32 v199, v199
	s_nop 0
	v_pk_fma_f32 v[200:201], v[198:199], s[92:93], v[178:179] op_sel_hi:[1,0,0]
	s_nop 0
	v_pk_fma_f32 v[200:201], v[198:199], v[200:201], s[96:97] op_sel_hi:[1,1,0]
	s_nop 0
	v_pk_fma_f32 v[200:201], v[198:199], v[200:201], s[44:45] op_sel_hi:[1,1,0]
	s_nop 0
	v_pk_fma_f32 v[200:201], v[198:199], v[200:201], s[58:59] op_sel_hi:[1,1,0]
	s_nop 0
	v_pk_mul_f32 v[198:199], v[198:199], v[200:201]
	v_pk_mul_f32 v[200:201], v[130:131], v[130:131]
	v_pk_fma_f32 v[198:199], v[202:203], v[198:199], 0.5 op_sel_hi:[1,1,0] neg_lo:[1,0,0] neg_hi:[1,0,0]
	s_nop 0
	v_pk_mul_f32 v[180:181], v[180:181], v[198:199]
	s_nop 0
	v_pk_fma_f32 v[128:129], v[128:129], 0.5, v[180:181] op_sel_hi:[1,0,1]
	v_and_b32_e32 v181, 0x7fffffff, v131
	v_and_b32_e32 v180, 0x7fffffff, v130
	v_pk_fma_f32 v[198:199], v[180:181], s[6:7], 1.0 op_sel_hi:[1,0,0]
	s_nop 0
	v_rcp_f32_e32 v198, v198
	v_rcp_f32_e32 v199, v199
	s_nop 0
	v_pk_fma_f32 v[178:179], v[198:199], s[92:93], v[178:179] op_sel_hi:[1,0,0]
	s_nop 0
	v_pk_fma_f32 v[178:179], v[198:199], v[178:179], s[96:97] op_sel_hi:[1,1,0]
	s_nop 0
	v_pk_fma_f32 v[178:179], v[198:199], v[178:179], s[44:45] op_sel_hi:[1,1,0]
	s_nop 0
	v_pk_fma_f32 v[178:179], v[198:199], v[178:179], s[58:59] op_sel_hi:[1,1,0]
	s_nop 0
	v_pk_mul_f32 v[178:179], v[198:199], v[178:179]
	v_pk_mul_f32 v[198:199], v[200:201], s[60:61] op_sel_hi:[1,0]
	s_nop 0
	v_exp_f32_e32 v198, v198
	v_exp_f32_e32 v199, v199
	s_nop 0
	v_pk_fma_f32 v[178:179], v[198:199], v[178:179], 0.5 op_sel_hi:[1,1,0] neg_lo:[1,0,0] neg_hi:[1,0,0]
	s_nop 0
	v_pk_mul_f32 v[178:179], v[180:181], v[178:179]
	v_cvt_pk_bf16_f32 v180, v128, v129
	s_nop 0
	v_pk_fma_f32 v[130:131], v[130:131], 0.5, v[178:179] op_sel_hi:[1,0,1]
	v_cvt_pk_bf16_f32 v178, v132, v133
	v_cvt_pk_bf16_f32 v179, v134, v135
	s_nop 0
	v_cvt_pk_bf16_f32 v181, v130, v131
	global_store_dwordx4 v[176:177], v[178:181], off offset:256
	s_cbranch_scc1 .LBB0_124
	v_pk_mul_f32 v[202:203], v[134:135], v[134:135]
	v_mov_b32_e32 v206, v132
	v_mov_b32_e32 v207, v134
	v_mov_b32_e32 v134, v133
	v_mov_b32_e32 v180, v141
	v_mov_b32_e32 v181, v143
	v_pk_mul_f32 v[200:201], v[132:133], v[132:133]
	v_pk_add_f32 v[132:133], v[206:207], v[134:135]
	v_mov_b32_e32 v178, v140
	v_mov_b32_e32 v179, v142
	v_pk_mul_f32 v[180:181], v[180:181], v[180:181]
	v_pk_add_f32 v[132:133], v[132:133], v[132:133] op_sel:[0,1] op_sel_hi:[1,0]
	v_pk_fma_f32 v[178:179], v[178:179], v[178:179], v[180:181]
	v_pk_mul_f32 v[204:205], v[128:129], v[128:129]
	v_pk_add_f32 v[140:141], v[140:141], v[140:141] op_sel:[0,1] op_sel_hi:[1,0]
	v_pk_add_f32 v[142:143], v[142:143], v[142:143] op_sel:[0,1] op_sel_hi:[1,0]
	v_pk_add_f32 v[128:129], v[128:129], v[128:129] op_sel:[0,1] op_sel_hi:[1,0]
	v_and_b32_e32 v133, 64, v189
	v_pk_add_f32 v[178:179], v[178:179], v[178:179] op_sel_hi:[0,1]
	v_xor_b32_e32 v129, 16, v189
	v_add_u32_e32 v197, 64, v133
	v_mov_b32_e32 v141, v200
	v_mov_b32_e32 v143, v201
	v_pk_mul_f32 v[176:177], v[138:139], v[138:139]
	v_mul_f32_e32 v178, v136, v136
	v_cmp_lt_i32_e32 vcc, v129, v197
	v_mov_b32_e32 v134, v138
	v_mov_b32_e32 v135, v204
	v_mov_b32_e32 v204, v139
	v_pk_add_f32 v[138:139], v[140:141], v[142:143]
	v_mov_b32_e32 v140, v136
	v_mov_b32_e32 v141, v202
	v_mov_b32_e32 v202, v137
	v_pk_fma_f32 v[180:181], v[136:137], v[136:137], v[178:179] op_sel_hi:[1,1,0]
	v_mul_f32_e32 v178, v130, v130
	v_cndmask_b32_e32 v129, v189, v129, vcc
	v_pk_add_f32 v[136:137], v[140:141], v[202:203]
	v_pk_fma_f32 v[198:199], v[130:131], v[130:131], v[178:179] op_sel_hi:[1,1,0]
	v_lshlrev_b32_e32 v206, 2, v129
	v_pk_add_f32 v[134:135], v[134:135], v[204:205]
	v_pk_add_f32 v[136:137], v[138:139], v[136:137]
	v_mov_b32_e32 v178, v130
	v_mov_b32_e32 v180, v131
	v_mov_b32_e32 v133, v176
	v_mov_b32_e32 v129, v177
	v_pk_add_f32 v[134:135], v[136:137], v[134:135]
	v_mov_b32_e32 v198, v145
	v_pk_add_f32 v[130:131], v[178:179], v[180:181]
	v_pk_add_f32 v[128:129], v[132:133], v[128:129]
	v_pk_add_f32 v[134:135], v[134:135], v[198:199]
	v_pk_add_f32 v[128:129], v[128:129], v[130:131]
	v_xor_b32_e32 v132, 32, v189
	v_pk_add_f32 v[128:129], v[128:129], v[134:135]
	ds_bpermute_b32 v130, v206, v128
	ds_bpermute_b32 v131, v206, v129
	v_cmp_lt_i32_e32 vcc, v132, v197
	s_waitcnt lgkmcnt(0)
	v_pk_add_f32 v[128:129], v[128:129], v[130:131]
	v_cndmask_b32_e32 v132, v189, v132, vcc
	v_lshlrev_b32_e32 v132, 2, v132
	ds_bpermute_b32 v130, v132, v128
	ds_bpermute_b32 v131, v132, v129
	s_and_saveexec_b64 s[6:7], s[0:1]
	s_cbranch_execz .LBB0_123
	v_lshlrev_b64 v[132:133], 8, v[174:175]
	s_waitcnt lgkmcnt(0)
	v_pk_add_f32 v[128:129], v[128:129], v[130:131]
	v_lshl_add_u64 v[130:131], s[16:17], 0, v[132:133]
	v_lshl_add_u64 v[130:131], s[26:27], 3, v[130:131]
	global_store_dwordx2 v[130:131], v[128:129], off

.LBB0_700:
	s_add_u32 s28, s26, 0xfff80080
	s_addc_u32 s29, s27, -1
	s_add_i32 s71, 0, 0x10000
	v_add_u32_e32 v172, s71, v143
	ds_read_b128 v[138:141], v172
	ds_read_b128 v[168:171], v172 offset:2048
	ds_read_b128 v[164:167], v172 offset:1024
	ds_read_b128 v[172:175], v172 offset:3072
	s_cmp_eq_u32 s70, 28
	s_cselect_b32 s31, s7, s29
	s_cselect_b32 s30, s6, s28
	s_cselect_b32 s29, s9, s67
	s_cselect_b32 s28, s8, s21
	v_lshl_add_u64 v[180:181], s[26:27], 0, v[134:135]
	s_add_i32 m0, s51, 0xc000
	ds_read_b128 v[176:179], v163
	ds_read_b128 v[198:201], v163 offset:2048
	ds_read_b128 v[206:209], v163 offset:4096
	ds_read_b128 v[214:217], v163 offset:6144
	ds_read_b128 v[194:197], v163 offset:1024
	ds_read_b128 v[202:205], v163 offset:3072
	ds_read_b128 v[210:213], v163 offset:5120
	ds_read_b128 v[218:221], v163 offset:7168
	global_load_lds_dwordx4 v[180:181], off
	v_lshl_add_u64 v[180:181], s[26:27], 0, v[136:137]
	s_add_i32 m0, s51, 0xe000
	s_nop 0
	global_load_lds_dwordx4 v[180:181], off
	s_barrier
	s_setprio 1
	s_waitcnt lgkmcnt(7)
	v_mfma_f32_16x16x32_bf16 v[124:127], v[138:141], v[176:179], v[124:127]
	v_mfma_f32_16x16x32_bf16 v[116:119], v[168:171], v[176:179], v[116:119]
	s_waitcnt lgkmcnt(6)
	v_mfma_f32_16x16x32_bf16 v[108:111], v[138:141], v[198:201], v[108:111]
	v_mfma_f32_16x16x32_bf16 v[100:103], v[168:171], v[198:201], v[100:103]
	s_waitcnt lgkmcnt(5)
	v_mfma_f32_16x16x32_bf16 v[92:95], v[138:141], v[206:209], v[92:95]
	v_mfma_f32_16x16x32_bf16 v[84:87], v[168:171], v[206:209], v[84:87]
	s_waitcnt lgkmcnt(4)
	v_mfma_f32_16x16x32_bf16 v[76:79], v[138:141], v[214:217], v[76:79]
	v_mfma_f32_16x16x32_bf16 v[68:71], v[168:171], v[214:217], v[68:71]
	s_waitcnt lgkmcnt(3)
	v_mfma_f32_16x16x32_bf16 v[124:127], v[164:167], v[194:197], v[124:127]
	v_mfma_f32_16x16x32_bf16 v[116:119], v[172:175], v[194:197], v[116:119]
	s_waitcnt lgkmcnt(2)
	v_mfma_f32_16x16x32_bf16 v[108:111], v[164:167], v[202:205], v[108:111]
	v_mfma_f32_16x16x32_bf16 v[100:103], v[172:175], v[202:205], v[100:103]
	s_waitcnt lgkmcnt(1)
	v_mfma_f32_16x16x32_bf16 v[92:95], v[164:167], v[210:213], v[92:95]
	v_mfma_f32_16x16x32_bf16 v[84:87], v[172:175], v[210:213], v[84:87]
	s_waitcnt lgkmcnt(0)
	v_mfma_f32_16x16x32_bf16 v[76:79], v[164:167], v[218:221], v[76:79]
	v_mfma_f32_16x16x32_bf16 v[68:71], v[172:175], v[218:221], v[68:71]
	s_setprio 0
	s_barrier
	s_add_i32 s74, 0, 0x14000
	v_add_u32_e32 v180, s74, v143
	s_add_i32 s71, s71, s50
	ds_read_b128 v[222:225], v180
	ds_read_b128 v[230:233], v180 offset:2048
	ds_read_b128 v[226:229], v180 offset:1024
	ds_read_b128 v[234:237], v180 offset:3072
	v_lshl_add_u64 v[180:181], s[28:29], 0, v[144:145]
	s_mov_b32 m0, s71
	v_lshl_add_u64 v[238:239], s[28:29], 0, v[128:129]
	global_load_lds_dwordx4 v[180:181], off
	s_add_i32 m0, s71, 0x2000
	s_nop 0
	global_load_lds_dwordx4 v[238:239], off
	s_barrier
	s_setprio 1
	s_waitcnt lgkmcnt(3)
	v_mfma_f32_16x16x32_bf16 v[120:123], v[222:225], v[176:179], v[120:123]
	s_waitcnt lgkmcnt(2)
	v_mfma_f32_16x16x32_bf16 v[112:115], v[230:233], v[176:179], v[112:115]
	v_mfma_f32_16x16x32_bf16 v[104:107], v[222:225], v[198:201], v[104:107]
	v_mfma_f32_16x16x32_bf16 v[96:99], v[230:233], v[198:201], v[96:99]
	v_mfma_f32_16x16x32_bf16 v[88:91], v[222:225], v[206:209], v[88:91]
	v_mfma_f32_16x16x32_bf16 v[80:83], v[230:233], v[206:209], v[80:83]
	v_mfma_f32_16x16x32_bf16 v[72:75], v[222:225], v[214:217], v[72:75]
	v_mfma_f32_16x16x32_bf16 v[64:67], v[230:233], v[214:217], v[64:67]
	s_waitcnt lgkmcnt(1)
	v_mfma_f32_16x16x32_bf16 v[120:123], v[226:229], v[194:197], v[120:123]
	s_waitcnt lgkmcnt(0)
	v_mfma_f32_16x16x32_bf16 v[112:115], v[234:237], v[194:197], v[112:115]
	v_mfma_f32_16x16x32_bf16 v[104:107], v[226:229], v[202:205], v[104:107]
	v_mfma_f32_16x16x32_bf16 v[96:99], v[234:237], v[202:205], v[96:99]
	v_mfma_f32_16x16x32_bf16 v[88:91], v[226:229], v[210:213], v[88:91]
	v_mfma_f32_16x16x32_bf16 v[80:83], v[234:237], v[210:213], v[80:83]
	v_mfma_f32_16x16x32_bf16 v[72:75], v[226:229], v[218:221], v[72:75]
	v_mfma_f32_16x16x32_bf16 v[64:67], v[234:237], v[218:221], v[64:67]
	s_setprio 0
	s_mov_b32 m0, s51
	v_lshl_add_u64 v[240:241], s[30:31], 0, v[132:133]
	s_barrier
	ds_read_b128 v[176:179], v163 offset:16384
	ds_read_b128 v[198:201], v163 offset:18432
	ds_read_b128 v[206:209], v163 offset:20480
	ds_read_b128 v[214:217], v163 offset:22528
	ds_read_b128 v[194:197], v163 offset:17408
	ds_read_b128 v[202:205], v163 offset:19456
	ds_read_b128 v[210:213], v163 offset:21504
	ds_read_b128 v[218:221], v163 offset:23552
	global_load_lds_dwordx4 v[240:241], off
	v_lshl_add_u64 v[242:243], s[30:31], 0, v[130:131]
	s_mov_b32 m0, s52
	s_nop 0
	global_load_lds_dwordx4 v[242:243], off
	s_barrier
	s_setprio 1
	s_waitcnt lgkmcnt(7)
	v_mfma_f32_16x16x32_bf16 v[60:63], v[138:141], v[176:179], v[60:63]
	v_mfma_f32_16x16x32_bf16 v[52:55], v[168:171], v[176:179], v[52:55]
	s_waitcnt lgkmcnt(6)
	v_mfma_f32_16x16x32_bf16 v[44:47], v[138:141], v[198:201], v[44:47]
	v_mfma_f32_16x16x32_bf16 v[36:39], v[168:171], v[198:201], v[36:39]
	s_waitcnt lgkmcnt(5)
	v_mfma_f32_16x16x32_bf16 v[28:31], v[138:141], v[206:209], v[28:31]
	v_mfma_f32_16x16x32_bf16 v[20:23], v[168:171], v[206:209], v[20:23]
	s_waitcnt lgkmcnt(4)
	v_mfma_f32_16x16x32_bf16 v[12:15], v[138:141], v[214:217], v[12:15]
	v_mfma_f32_16x16x32_bf16 v[4:7], v[168:171], v[214:217], v[4:7]
	s_waitcnt lgkmcnt(3)
	v_mfma_f32_16x16x32_bf16 v[60:63], v[164:167], v[194:197], v[60:63]
	v_mfma_f32_16x16x32_bf16 v[52:55], v[172:175], v[194:197], v[52:55]
	s_waitcnt lgkmcnt(2)
	v_mfma_f32_16x16x32_bf16 v[44:47], v[164:167], v[202:205], v[44:47]
	v_mfma_f32_16x16x32_bf16 v[36:39], v[172:175], v[202:205], v[36:39]
	s_waitcnt lgkmcnt(1)
	v_mfma_f32_16x16x32_bf16 v[28:31], v[164:167], v[210:213], v[28:31]
	v_mfma_f32_16x16x32_bf16 v[20:23], v[172:175], v[210:213], v[20:23]
	s_waitcnt lgkmcnt(0)
	v_mfma_f32_16x16x32_bf16 v[12:15], v[164:167], v[218:221], v[12:15]
	v_mfma_f32_16x16x32_bf16 v[4:7], v[172:175], v[218:221], v[4:7]
	s_setprio 0
	s_barrier
	s_add_u32 s72, s28, 0x80000
	s_addc_u32 s73, s29, 0
	s_add_i32 s71, s74, s50
	v_lshl_add_u64 v[138:139], s[72:73], 0, v[144:145]
	s_mov_b32 m0, s71
	s_nop 0
	global_load_lds_dwordx4 v[138:139], off
	v_lshl_add_u64 v[138:139], s[72:73], 0, v[128:129]
	s_add_i32 m0, s71, 0x2000
	s_nop 0
	global_load_lds_dwordx4 v[138:139], off
	s_waitcnt vmcnt(6)
	s_barrier
	s_setprio 1
	v_mfma_f32_16x16x32_bf16 v[56:59], v[222:225], v[176:179], v[56:59]
	v_mfma_f32_16x16x32_bf16 v[48:51], v[230:233], v[176:179], v[48:51]
	v_mfma_f32_16x16x32_bf16 v[40:43], v[222:225], v[198:201], v[40:43]
	v_mfma_f32_16x16x32_bf16 v[32:35], v[230:233], v[198:201], v[32:35]
	v_mfma_f32_16x16x32_bf16 v[24:27], v[222:225], v[206:209], v[24:27]
	v_mfma_f32_16x16x32_bf16 v[16:19], v[230:233], v[206:209], v[16:19]
	v_mfma_f32_16x16x32_bf16 v[8:11], v[222:225], v[214:217], v[8:11]
	v_mfma_f32_16x16x32_bf16 v[0:3], v[230:233], v[214:217], v[0:3]
	v_mfma_f32_16x16x32_bf16 v[56:59], v[226:229], v[194:197], v[56:59]
	v_mfma_f32_16x16x32_bf16 v[48:51], v[234:237], v[194:197], v[48:51]
	v_mfma_f32_16x16x32_bf16 v[40:43], v[226:229], v[202:205], v[40:43]
	v_mfma_f32_16x16x32_bf16 v[32:35], v[234:237], v[202:205], v[32:35]
	v_mfma_f32_16x16x32_bf16 v[24:27], v[226:229], v[210:213], v[24:27]
	v_mfma_f32_16x16x32_bf16 v[16:19], v[234:237], v[210:213], v[16:19]
	v_mfma_f32_16x16x32_bf16 v[8:11], v[226:229], v[218:221], v[8:11]
	v_mfma_f32_16x16x32_bf16 v[0:3], v[234:237], v[218:221], v[0:3]
	s_setprio 0
	s_add_i32 s71, 0, 0x18000
	v_add_u32_e32 v172, s71, v143
	s_barrier
	ds_read_b128 v[138:141], v172
	ds_read_b128 v[168:171], v172 offset:2048
	ds_read_b128 v[164:167], v172 offset:1024
	ds_read_b128 v[172:175], v172 offset:3072
	s_add_u32 s30, s30, 0x80000
	s_addc_u32 s31, s31, 0
	s_mov_b32 m0, s53
	v_lshl_add_u64 v[222:223], s[30:31], 0, v[132:133]
	ds_read_b128 v[176:179], v163 offset:32768
	ds_read_b128 v[198:201], v163 offset:34816
	ds_read_b128 v[206:209], v163 offset:36864
	ds_read_b128 v[214:217], v163 offset:38912
	ds_read_b128 v[194:197], v163 offset:33792
	ds_read_b128 v[202:205], v163 offset:35840
	ds_read_b128 v[210:213], v163 offset:37888
	ds_read_b128 v[218:221], v163 offset:39936
	global_load_lds_dwordx4 v[222:223], off
	v_lshl_add_u64 v[222:223], s[30:31], 0, v[130:131]
	s_mov_b32 m0, s54
	s_nop 0
	global_load_lds_dwordx4 v[222:223], off
	s_barrier
	s_setprio 1
	s_waitcnt lgkmcnt(7)
	v_mfma_f32_16x16x32_bf16 v[124:127], v[138:141], v[176:179], v[124:127]
	v_mfma_f32_16x16x32_bf16 v[116:119], v[168:171], v[176:179], v[116:119]
	s_waitcnt lgkmcnt(6)
	v_mfma_f32_16x16x32_bf16 v[108:111], v[138:141], v[198:201], v[108:111]
	v_mfma_f32_16x16x32_bf16 v[100:103], v[168:171], v[198:201], v[100:103]
	s_waitcnt lgkmcnt(5)
	v_mfma_f32_16x16x32_bf16 v[92:95], v[138:141], v[206:209], v[92:95]
	v_mfma_f32_16x16x32_bf16 v[84:87], v[168:171], v[206:209], v[84:87]
	s_waitcnt lgkmcnt(4)
	v_mfma_f32_16x16x32_bf16 v[76:79], v[138:141], v[214:217], v[76:79]
	v_mfma_f32_16x16x32_bf16 v[68:71], v[168:171], v[214:217], v[68:71]
	s_waitcnt lgkmcnt(3)
	v_mfma_f32_16x16x32_bf16 v[124:127], v[164:167], v[194:197], v[124:127]
	v_mfma_f32_16x16x32_bf16 v[116:119], v[172:175], v[194:197], v[116:119]
	s_waitcnt lgkmcnt(2)
	v_mfma_f32_16x16x32_bf16 v[108:111], v[164:167], v[202:205], v[108:111]
	v_mfma_f32_16x16x32_bf16 v[100:103], v[172:175], v[202:205], v[100:103]
	s_waitcnt lgkmcnt(1)
	v_mfma_f32_16x16x32_bf16 v[92:95], v[164:167], v[210:213], v[92:95]
	v_mfma_f32_16x16x32_bf16 v[84:87], v[172:175], v[210:213], v[84:87]
	s_waitcnt lgkmcnt(0)
	v_mfma_f32_16x16x32_bf16 v[76:79], v[164:167], v[218:221], v[76:79]
	v_mfma_f32_16x16x32_bf16 v[68:71], v[172:175], v[218:221], v[68:71]
	s_setprio 0
	s_barrier
	s_add_i32 s30, 0, 0x1c000
	s_add_i32 s31, s71, s50
	v_add_u32_e32 v193, s30, v143
	v_lshl_add_u64 v[180:181], v[180:181], 0, s[86:87]
	s_mov_b32 m0, s31
	ds_read_b128 v[222:225], v193
	ds_read_b128 v[230:233], v193 offset:2048
	ds_read_b128 v[226:229], v193 offset:1024
	ds_read_b128 v[234:237], v193 offset:3072
	global_load_lds_dwordx4 v[180:181], off
	v_lshl_add_u64 v[180:181], v[238:239], 0, s[86:87]
	s_add_i32 m0, s31, 0x2000
	s_nop 0
	global_load_lds_dwordx4 v[180:181], off
	s_barrier
	s_setprio 1
	s_waitcnt lgkmcnt(3)
	v_mfma_f32_16x16x32_bf16 v[120:123], v[222:225], v[176:179], v[120:123]
	s_waitcnt lgkmcnt(2)
	v_mfma_f32_16x16x32_bf16 v[112:115], v[230:233], v[176:179], v[112:115]
	v_mfma_f32_16x16x32_bf16 v[104:107], v[222:225], v[198:201], v[104:107]
	v_mfma_f32_16x16x32_bf16 v[96:99], v[230:233], v[198:201], v[96:99]
	v_mfma_f32_16x16x32_bf16 v[88:91], v[222:225], v[206:209], v[88:91]
	v_mfma_f32_16x16x32_bf16 v[80:83], v[230:233], v[206:209], v[80:83]
	v_mfma_f32_16x16x32_bf16 v[72:75], v[222:225], v[214:217], v[72:75]
	v_mfma_f32_16x16x32_bf16 v[64:67], v[230:233], v[214:217], v[64:67]
	s_waitcnt lgkmcnt(1)
	v_mfma_f32_16x16x32_bf16 v[120:123], v[226:229], v[194:197], v[120:123]
	s_waitcnt lgkmcnt(0)
	v_mfma_f32_16x16x32_bf16 v[112:115], v[234:237], v[194:197], v[112:115]
	v_mfma_f32_16x16x32_bf16 v[104:107], v[226:229], v[202:205], v[104:107]
	v_mfma_f32_16x16x32_bf16 v[96:99], v[234:237], v[202:205], v[96:99]
	v_mfma_f32_16x16x32_bf16 v[88:91], v[226:229], v[210:213], v[88:91]
	v_mfma_f32_16x16x32_bf16 v[80:83], v[234:237], v[210:213], v[80:83]
	v_mfma_f32_16x16x32_bf16 v[72:75], v[226:229], v[218:221], v[72:75]
	v_mfma_f32_16x16x32_bf16 v[64:67], v[234:237], v[218:221], v[64:67]
	s_setprio 0
	s_mov_b32 m0, s12
	v_lshl_add_u64 v[180:181], v[240:241], 0, s[86:87]
	s_barrier
	ds_read_b128 v[176:179], v163 offset:49152
	ds_read_b128 v[198:201], v163 offset:51200
	ds_read_b128 v[206:209], v163 offset:53248
	ds_read_b128 v[214:217], v163 offset:55296
	ds_read_b128 v[194:197], v163 offset:50176
	ds_read_b128 v[202:205], v163 offset:52224
	ds_read_b128 v[210:213], v163 offset:54272
	ds_read_b128 v[218:221], v163 offset:56320
	global_load_lds_dwordx4 v[180:181], off
	v_lshl_add_u64 v[180:181], v[242:243], 0, s[86:87]
	s_mov_b32 m0, s13
	s_nop 0
	global_load_lds_dwordx4 v[180:181], off
	s_barrier
	s_setprio 1
	s_waitcnt lgkmcnt(7)
	v_mfma_f32_16x16x32_bf16 v[60:63], v[138:141], v[176:179], v[60:63]
	v_mfma_f32_16x16x32_bf16 v[52:55], v[168:171], v[176:179], v[52:55]
	s_waitcnt lgkmcnt(6)
	v_mfma_f32_16x16x32_bf16 v[44:47], v[138:141], v[198:201], v[44:47]
	v_mfma_f32_16x16x32_bf16 v[36:39], v[168:171], v[198:201], v[36:39]
	s_waitcnt lgkmcnt(5)
	v_mfma_f32_16x16x32_bf16 v[28:31], v[138:141], v[206:209], v[28:31]
	v_mfma_f32_16x16x32_bf16 v[20:23], v[168:171], v[206:209], v[20:23]
	s_waitcnt lgkmcnt(4)
	v_mfma_f32_16x16x32_bf16 v[12:15], v[138:141], v[214:217], v[12:15]
	v_mfma_f32_16x16x32_bf16 v[4:7], v[168:171], v[214:217], v[4:7]
	s_waitcnt lgkmcnt(3)
	v_mfma_f32_16x16x32_bf16 v[60:63], v[164:167], v[194:197], v[60:63]
	v_mfma_f32_16x16x32_bf16 v[52:55], v[172:175], v[194:197], v[52:55]
	s_waitcnt lgkmcnt(2)
	v_mfma_f32_16x16x32_bf16 v[44:47], v[164:167], v[202:205], v[44:47]
	v_mfma_f32_16x16x32_bf16 v[36:39], v[172:175], v[202:205], v[36:39]
	s_waitcnt lgkmcnt(1)
	v_mfma_f32_16x16x32_bf16 v[28:31], v[164:167], v[210:213], v[28:31]
	v_mfma_f32_16x16x32_bf16 v[20:23], v[172:175], v[210:213], v[20:23]
	s_waitcnt lgkmcnt(0)
	v_mfma_f32_16x16x32_bf16 v[12:15], v[164:167], v[218:221], v[12:15]
	v_mfma_f32_16x16x32_bf16 v[4:7], v[172:175], v[218:221], v[4:7]
	s_setprio 0
	s_barrier
	s_add_u32 s28, s28, 0x80080
	s_addc_u32 s29, s29, 0
	s_add_i32 s30, s30, s50
	v_lshl_add_u64 v[138:139], s[28:29], 0, v[144:145]
	s_mov_b32 m0, s30
	s_nop 0
	global_load_lds_dwordx4 v[138:139], off
	v_lshl_add_u64 v[138:139], s[28:29], 0, v[128:129]
	s_add_i32 m0, s30, 0x2000
	s_nop 0
	global_load_lds_dwordx4 v[138:139], off
	s_waitcnt vmcnt(6)
	s_barrier
	s_setprio 1
	v_mfma_f32_16x16x32_bf16 v[56:59], v[222:225], v[176:179], v[56:59]
	v_mfma_f32_16x16x32_bf16 v[48:51], v[230:233], v[176:179], v[48:51]
	v_mfma_f32_16x16x32_bf16 v[40:43], v[222:225], v[198:201], v[40:43]
	v_mfma_f32_16x16x32_bf16 v[32:35], v[230:233], v[198:201], v[32:35]
	v_mfma_f32_16x16x32_bf16 v[24:27], v[222:225], v[206:209], v[24:27]
	v_mfma_f32_16x16x32_bf16 v[16:19], v[230:233], v[206:209], v[16:19]
	v_mfma_f32_16x16x32_bf16 v[8:11], v[222:225], v[214:217], v[8:11]
	v_mfma_f32_16x16x32_bf16 v[0:3], v[230:233], v[214:217], v[0:3]
	v_mfma_f32_16x16x32_bf16 v[56:59], v[226:229], v[194:197], v[56:59]
	v_mfma_f32_16x16x32_bf16 v[48:51], v[234:237], v[194:197], v[48:51]
	v_mfma_f32_16x16x32_bf16 v[40:43], v[226:229], v[202:205], v[40:43]
	v_mfma_f32_16x16x32_bf16 v[32:35], v[234:237], v[202:205], v[32:35]
	v_mfma_f32_16x16x32_bf16 v[24:27], v[226:229], v[210:213], v[24:27]
	v_mfma_f32_16x16x32_bf16 v[16:19], v[234:237], v[210:213], v[16:19]
	v_mfma_f32_16x16x32_bf16 v[8:11], v[226:229], v[218:221], v[8:11]
	v_mfma_f32_16x16x32_bf16 v[0:3], v[234:237], v[218:221], v[0:3]
	s_setprio 0
	s_add_i32 s70, s70, 2
	s_add_u32 s26, s26, 0x100
	s_addc_u32 s27, s27, 0
	s_add_u32 s21, s21, 0x100
	s_addc_u32 s67, s67, 0
	s_cmp_gt_u32 s70, 29
	s_barrier
	s_cbranch_scc0 .LBB0_700
	v_pk_mul_f32 v[168:169], v[126:127], s[48:49] op_sel_hi:[1,0]
	v_pk_mul_f32 v[170:171], v[124:125], s[48:49] op_sel_hi:[1,0]
	v_exp_f32_e32 v168, v168
	v_exp_f32_e32 v170, v170
	v_exp_f32_e32 v171, v171
	v_exp_f32_e32 v169, v169
	v_pk_mul_f32 v[122:123], v[126:127], v[122:123]
	v_pk_mul_f32 v[120:121], v[124:125], v[120:121]
	v_pk_add_f32 v[170:171], v[170:171], 1.0 op_sel_hi:[1,0]
	v_pk_add_f32 v[168:169], v[168:169], 1.0 op_sel_hi:[1,0]
	v_rcp_f32_e32 v124, v170
	v_rcp_f32_e32 v125, v171
	v_rcp_f32_e32 v126, v168
	v_rcp_f32_e32 v127, v169
	v_pk_mul_f32 v[114:115], v[118:119], v[114:115]
	v_pk_mul_f32 v[120:121], v[124:125], v[120:121]
	v_pk_mul_f32 v[124:125], v[118:119], s[48:49] op_sel_hi:[1,0]
	v_pk_mul_f32 v[122:123], v[126:127], v[122:123]
	v_pk_mul_f32 v[126:127], v[116:117], s[48:49] op_sel_hi:[1,0]
	v_exp_f32_e32 v124, v124
	v_exp_f32_e32 v126, v126
	v_exp_f32_e32 v127, v127
	v_exp_f32_e32 v125, v125
	v_pk_mul_f32 v[112:113], v[116:117], v[112:113]
	v_lshl_or_b32 v140, s57, 7, v162
	v_pk_add_f32 v[126:127], v[126:127], 1.0 op_sel_hi:[1,0]
	v_pk_add_f32 v[124:125], v[124:125], 1.0 op_sel_hi:[1,0]
	v_rcp_f32_e32 v116, v126
	v_rcp_f32_e32 v117, v127
	v_rcp_f32_e32 v118, v124
	v_rcp_f32_e32 v119, v125
	v_lshl_add_u32 v164, s66, 8, v142
	v_ashrrev_i32_e32 v141, 31, v140
	v_mov_b64_e32 v[138:139], s[10:11]
	v_mad_i64_i32 v[166:167], s[26:27], v164, s90, v[138:139]
	v_lshlrev_b64 v[140:141], 1, v[140:141]
	v_pk_mul_f32 v[118:119], v[118:119], v[114:115]
	v_pk_mul_f32 v[114:115], v[116:117], v[112:113]
	v_lshl_add_u64 v[166:167], v[166:167], 0, v[140:141]
	v_cvt_pk_bf16_f32 v114, v114, v115
	v_cvt_pk_bf16_f32 v115, v118, v119
	v_cvt_pk_bf16_f32 v112, v120, v121
	v_cvt_pk_bf16_f32 v113, v122, v123
	global_store_dwordx4 v[166:167], v[112:115], off
	v_pk_mul_f32 v[116:117], v[108:109], s[48:49] op_sel_hi:[1,0]
	v_pk_mul_f32 v[106:107], v[110:111], v[106:107]
	v_pk_mul_f32 v[114:115], v[110:111], s[48:49] op_sel_hi:[1,0]
	v_exp_f32_e32 v116, v116
	v_exp_f32_e32 v117, v117
	v_exp_f32_e32 v114, v114
	v_exp_f32_e32 v115, v115
	v_pk_mul_f32 v[104:105], v[108:109], v[104:105]
	v_pk_add_f32 v[116:117], v[116:117], 1.0 op_sel_hi:[1,0]
	v_pk_mul_f32 v[98:99], v[102:103], v[98:99]
	v_pk_add_f32 v[114:115], v[114:115], 1.0 op_sel_hi:[1,0]
	v_rcp_f32_e32 v108, v116
	v_rcp_f32_e32 v109, v117
	v_rcp_f32_e32 v110, v114
	v_rcp_f32_e32 v111, v115
	v_pk_mul_f32 v[96:97], v[100:101], v[96:97]
	v_pk_mul_f32 v[104:105], v[108:109], v[104:105]
	v_pk_mul_f32 v[108:109], v[102:103], s[48:49] op_sel_hi:[1,0]
	v_pk_mul_f32 v[106:107], v[110:111], v[106:107]
	v_pk_mul_f32 v[110:111], v[100:101], s[48:49] op_sel_hi:[1,0]
	v_exp_f32_e32 v108, v108
	v_exp_f32_e32 v110, v110
	v_exp_f32_e32 v111, v111
	v_exp_f32_e32 v109, v109
	v_or_b32_e32 v112, 16, v164
	v_mad_i64_i32 v[112:113], s[26:27], v112, s90, v[138:139]
	v_pk_add_f32 v[108:109], v[108:109], 1.0 op_sel_hi:[1,0]
	v_pk_add_f32 v[110:111], v[110:111], 1.0 op_sel_hi:[1,0]
	v_rcp_f32_e32 v102, v108
	v_rcp_f32_e32 v100, v110
	v_rcp_f32_e32 v101, v111
	v_rcp_f32_e32 v103, v109
	v_lshl_add_u64 v[112:113], v[112:113], 0, v[140:141]
	v_pk_mul_f32 v[90:91], v[94:95], v[90:91]
	v_pk_mul_f32 v[88:89], v[92:93], v[88:89]
	v_pk_mul_f32 v[102:103], v[102:103], v[98:99]
	v_pk_mul_f32 v[98:99], v[100:101], v[96:97]
	v_cvt_pk_bf16_f32 v96, v104, v105
	v_cvt_pk_bf16_f32 v97, v106, v107
	v_pk_mul_f32 v[100:101], v[92:93], s[48:49] op_sel_hi:[1,0]
	v_cvt_pk_bf16_f32 v98, v98, v99
	v_cvt_pk_bf16_f32 v99, v102, v103
	global_store_dwordx4 v[112:113], v[96:99], off
	v_exp_f32_e32 v100, v100
	v_exp_f32_e32 v101, v101
	v_pk_mul_f32 v[98:99], v[94:95], s[48:49] op_sel_hi:[1,0]
	v_pk_mul_f32 v[82:83], v[86:87], v[82:83]
	v_exp_f32_e32 v98, v98
	v_exp_f32_e32 v99, v99
	v_pk_add_f32 v[100:101], v[100:101], 1.0 op_sel_hi:[1,0]
	v_pk_mul_f32 v[80:81], v[84:85], v[80:81]
	v_rcp_f32_e32 v92, v100
	v_pk_add_f32 v[98:99], v[98:99], 1.0 op_sel_hi:[1,0]
	v_rcp_f32_e32 v93, v101
	v_rcp_f32_e32 v94, v98
	v_rcp_f32_e32 v95, v99
	v_or_b32_e32 v96, 32, v164
	v_pk_mul_f32 v[88:89], v[92:93], v[88:89]
	v_pk_mul_f32 v[92:93], v[86:87], s[48:49] op_sel_hi:[1,0]
	v_pk_mul_f32 v[90:91], v[94:95], v[90:91]
	v_pk_mul_f32 v[94:95], v[84:85], s[48:49] op_sel_hi:[1,0]
	v_exp_f32_e32 v92, v92
	v_exp_f32_e32 v94, v94
	v_exp_f32_e32 v95, v95
	v_exp_f32_e32 v93, v93
	v_mad_i64_i32 v[96:97], s[26:27], v96, s90, v[138:139]
	v_pk_add_f32 v[94:95], v[94:95], 1.0 op_sel_hi:[1,0]
	v_pk_add_f32 v[92:93], v[92:93], 1.0 op_sel_hi:[1,0]
	v_rcp_f32_e32 v84, v94
	v_rcp_f32_e32 v85, v95
	v_rcp_f32_e32 v86, v92
	v_rcp_f32_e32 v87, v93
	v_lshl_add_u64 v[96:97], v[96:97], 0, v[140:141]
	v_pk_mul_f32 v[74:75], v[78:79], v[74:75]
	v_pk_mul_f32 v[72:73], v[76:77], v[72:73]
	v_pk_mul_f32 v[86:87], v[86:87], v[82:83]
	v_pk_mul_f32 v[82:83], v[84:85], v[80:81]
	v_cvt_pk_bf16_f32 v80, v88, v89
	v_cvt_pk_bf16_f32 v81, v90, v91
	v_pk_mul_f32 v[84:85], v[76:77], s[48:49] op_sel_hi:[1,0]
	v_cvt_pk_bf16_f32 v82, v82, v83
	v_cvt_pk_bf16_f32 v83, v86, v87
	global_store_dwordx4 v[96:97], v[80:83], off
	v_exp_f32_e32 v84, v84
	v_exp_f32_e32 v85, v85
	v_pk_mul_f32 v[82:83], v[78:79], s[48:49] op_sel_hi:[1,0]
	v_pk_mul_f32 v[66:67], v[70:71], v[66:67]
	v_exp_f32_e32 v82, v82
	v_exp_f32_e32 v83, v83
	v_pk_add_f32 v[84:85], v[84:85], 1.0 op_sel_hi:[1,0]
	v_pk_mul_f32 v[64:65], v[68:69], v[64:65]
	v_rcp_f32_e32 v76, v84
	v_pk_add_f32 v[82:83], v[82:83], 1.0 op_sel_hi:[1,0]
	v_rcp_f32_e32 v77, v85
	v_rcp_f32_e32 v78, v82
	v_rcp_f32_e32 v79, v83
	v_or_b32_e32 v80, 48, v164
	v_pk_mul_f32 v[72:73], v[76:77], v[72:73]
	v_pk_mul_f32 v[76:77], v[70:71], s[48:49] op_sel_hi:[1,0]
	v_pk_mul_f32 v[74:75], v[78:79], v[74:75]
	v_pk_mul_f32 v[78:79], v[68:69], s[48:49] op_sel_hi:[1,0]
	v_exp_f32_e32 v76, v76
	v_exp_f32_e32 v78, v78
	v_exp_f32_e32 v79, v79
	v_exp_f32_e32 v77, v77
	v_mad_i64_i32 v[80:81], s[26:27], v80, s90, v[138:139]
	v_pk_add_f32 v[78:79], v[78:79], 1.0 op_sel_hi:[1,0]
	v_pk_add_f32 v[76:77], v[76:77], 1.0 op_sel_hi:[1,0]
	v_rcp_f32_e32 v68, v78
	v_rcp_f32_e32 v69, v79
	v_rcp_f32_e32 v70, v76
	v_rcp_f32_e32 v71, v77
	v_lshl_add_u64 v[80:81], v[80:81], 0, v[140:141]
	v_pk_mul_f32 v[58:59], v[62:63], v[58:59]
	v_pk_mul_f32 v[56:57], v[60:61], v[56:57]
	v_pk_mul_f32 v[70:71], v[70:71], v[66:67]
	v_pk_mul_f32 v[66:67], v[68:69], v[64:65]
	v_cvt_pk_bf16_f32 v64, v72, v73
	v_cvt_pk_bf16_f32 v65, v74, v75
	v_pk_mul_f32 v[68:69], v[60:61], s[48:49] op_sel_hi:[1,0]
	v_cvt_pk_bf16_f32 v66, v66, v67
	v_cvt_pk_bf16_f32 v67, v70, v71
	global_store_dwordx4 v[80:81], v[64:67], off
	v_exp_f32_e32 v68, v68
	v_exp_f32_e32 v69, v69
	v_pk_mul_f32 v[66:67], v[62:63], s[48:49] op_sel_hi:[1,0]
	v_pk_mul_f32 v[50:51], v[54:55], v[50:51]
	v_exp_f32_e32 v66, v66
	v_exp_f32_e32 v67, v67
	v_pk_add_f32 v[68:69], v[68:69], 1.0 op_sel_hi:[1,0]
	v_pk_mul_f32 v[48:49], v[52:53], v[48:49]
	v_rcp_f32_e32 v60, v68
	v_pk_add_f32 v[66:67], v[66:67], 1.0 op_sel_hi:[1,0]
	v_rcp_f32_e32 v61, v69
	v_rcp_f32_e32 v62, v66
	v_rcp_f32_e32 v63, v67
	v_add_u32_e32 v64, 0x80, v164
	v_pk_mul_f32 v[56:57], v[60:61], v[56:57]
	v_pk_mul_f32 v[60:61], v[54:55], s[48:49] op_sel_hi:[1,0]
	v_pk_mul_f32 v[58:59], v[62:63], v[58:59]
	v_pk_mul_f32 v[62:63], v[52:53], s[48:49] op_sel_hi:[1,0]
	v_exp_f32_e32 v60, v60
	v_exp_f32_e32 v62, v62
	v_exp_f32_e32 v63, v63
	v_exp_f32_e32 v61, v61
	v_mad_i64_i32 v[64:65], s[26:27], v64, s90, v[138:139]
	v_pk_add_f32 v[62:63], v[62:63], 1.0 op_sel_hi:[1,0]
	v_pk_add_f32 v[60:61], v[60:61], 1.0 op_sel_hi:[1,0]
	v_rcp_f32_e32 v52, v62
	v_rcp_f32_e32 v53, v63
	v_rcp_f32_e32 v54, v60
	v_rcp_f32_e32 v55, v61
	v_lshl_add_u64 v[64:65], v[64:65], 0, v[140:141]
	v_pk_mul_f32 v[42:43], v[46:47], v[42:43]
	v_pk_mul_f32 v[40:41], v[44:45], v[40:41]
	v_pk_mul_f32 v[54:55], v[54:55], v[50:51]
	v_pk_mul_f32 v[50:51], v[52:53], v[48:49]
	v_cvt_pk_bf16_f32 v48, v56, v57
	v_cvt_pk_bf16_f32 v49, v58, v59
	v_pk_mul_f32 v[52:53], v[44:45], s[48:49] op_sel_hi:[1,0]
	v_cvt_pk_bf16_f32 v50, v50, v51
	v_cvt_pk_bf16_f32 v51, v54, v55
	global_store_dwordx4 v[64:65], v[48:51], off
	v_exp_f32_e32 v52, v52
	v_exp_f32_e32 v53, v53
	v_pk_mul_f32 v[50:51], v[46:47], s[48:49] op_sel_hi:[1,0]
	v_pk_mul_f32 v[34:35], v[38:39], v[34:35]
	v_exp_f32_e32 v50, v50
	v_exp_f32_e32 v51, v51
	v_pk_add_f32 v[52:53], v[52:53], 1.0 op_sel_hi:[1,0]
	v_pk_mul_f32 v[32:33], v[36:37], v[32:33]
	v_rcp_f32_e32 v44, v52
	v_pk_add_f32 v[50:51], v[50:51], 1.0 op_sel_hi:[1,0]
	v_rcp_f32_e32 v45, v53
	v_rcp_f32_e32 v46, v50
	v_rcp_f32_e32 v47, v51
	v_add_u32_e32 v48, 0x90, v164
	v_pk_mul_f32 v[40:41], v[44:45], v[40:41]
	v_pk_mul_f32 v[44:45], v[38:39], s[48:49] op_sel_hi:[1,0]
	v_pk_mul_f32 v[42:43], v[46:47], v[42:43]
	v_pk_mul_f32 v[46:47], v[36:37], s[48:49] op_sel_hi:[1,0]
	v_exp_f32_e32 v44, v44
	v_exp_f32_e32 v46, v46
	v_exp_f32_e32 v47, v47
	v_exp_f32_e32 v45, v45
	v_mad_i64_i32 v[48:49], s[26:27], v48, s90, v[138:139]
	v_pk_add_f32 v[46:47], v[46:47], 1.0 op_sel_hi:[1,0]
	v_pk_add_f32 v[44:45], v[44:45], 1.0 op_sel_hi:[1,0]
	v_rcp_f32_e32 v36, v46
	v_rcp_f32_e32 v37, v47
	v_rcp_f32_e32 v38, v44
	v_rcp_f32_e32 v39, v45
	v_lshl_add_u64 v[48:49], v[48:49], 0, v[140:141]
	v_pk_mul_f32 v[26:27], v[30:31], v[26:27]
	v_pk_mul_f32 v[24:25], v[28:29], v[24:25]
	v_pk_mul_f32 v[38:39], v[38:39], v[34:35]
	v_pk_mul_f32 v[34:35], v[36:37], v[32:33]
	v_cvt_pk_bf16_f32 v32, v40, v41
	v_cvt_pk_bf16_f32 v33, v42, v43
	v_pk_mul_f32 v[36:37], v[28:29], s[48:49] op_sel_hi:[1,0]
	v_cvt_pk_bf16_f32 v34, v34, v35
	v_cvt_pk_bf16_f32 v35, v38, v39
	global_store_dwordx4 v[48:49], v[32:35], off
	v_exp_f32_e32 v36, v36
	v_exp_f32_e32 v37, v37
	v_pk_mul_f32 v[34:35], v[30:31], s[48:49] op_sel_hi:[1,0]
	v_pk_mul_f32 v[18:19], v[22:23], v[18:19]
	v_exp_f32_e32 v34, v34
	v_exp_f32_e32 v35, v35
	v_pk_add_f32 v[36:37], v[36:37], 1.0 op_sel_hi:[1,0]
	v_pk_mul_f32 v[16:17], v[20:21], v[16:17]
	v_rcp_f32_e32 v28, v36
	v_pk_add_f32 v[34:35], v[34:35], 1.0 op_sel_hi:[1,0]
	v_rcp_f32_e32 v29, v37
	v_rcp_f32_e32 v30, v34
	v_rcp_f32_e32 v31, v35
	v_add_u32_e32 v32, 0xa0, v164
	v_pk_mul_f32 v[24:25], v[28:29], v[24:25]
	v_pk_mul_f32 v[28:29], v[22:23], s[48:49] op_sel_hi:[1,0]
	v_pk_mul_f32 v[26:27], v[30:31], v[26:27]
	v_pk_mul_f32 v[30:31], v[20:21], s[48:49] op_sel_hi:[1,0]
	v_exp_f32_e32 v28, v28
	v_exp_f32_e32 v30, v30
	v_exp_f32_e32 v31, v31
	v_exp_f32_e32 v29, v29
	v_mad_i64_i32 v[32:33], s[26:27], v32, s90, v[138:139]
	v_pk_add_f32 v[30:31], v[30:31], 1.0 op_sel_hi:[1,0]
	v_pk_add_f32 v[28:29], v[28:29], 1.0 op_sel_hi:[1,0]
	v_rcp_f32_e32 v20, v30
	v_rcp_f32_e32 v21, v31
	v_rcp_f32_e32 v22, v28
	v_rcp_f32_e32 v23, v29
	v_lshl_add_u64 v[32:33], v[32:33], 0, v[140:141]
	v_pk_mul_f32 v[10:11], v[14:15], v[10:11]
	v_pk_mul_f32 v[8:9], v[12:13], v[8:9]
	v_pk_mul_f32 v[22:23], v[22:23], v[18:19]
	v_pk_mul_f32 v[18:19], v[20:21], v[16:17]
	v_cvt_pk_bf16_f32 v16, v24, v25
	v_cvt_pk_bf16_f32 v17, v26, v27
	v_pk_mul_f32 v[20:21], v[12:13], s[48:49] op_sel_hi:[1,0]
	v_cvt_pk_bf16_f32 v18, v18, v19
	v_cvt_pk_bf16_f32 v19, v22, v23
	global_store_dwordx4 v[32:33], v[16:19], off
	v_exp_f32_e32 v20, v20
	v_exp_f32_e32 v21, v21
	v_pk_mul_f32 v[18:19], v[14:15], s[48:49] op_sel_hi:[1,0]
	v_pk_mul_f32 v[2:3], v[6:7], v[2:3]
	v_exp_f32_e32 v18, v18
	v_exp_f32_e32 v19, v19
	v_pk_add_f32 v[20:21], v[20:21], 1.0 op_sel_hi:[1,0]
	v_pk_mul_f32 v[0:1], v[4:5], v[0:1]
	v_rcp_f32_e32 v12, v20
	v_pk_add_f32 v[18:19], v[18:19], 1.0 op_sel_hi:[1,0]
	v_rcp_f32_e32 v13, v21
	v_rcp_f32_e32 v14, v18
	v_rcp_f32_e32 v15, v19
	v_add_u32_e32 v16, 0xb0, v164
	v_pk_mul_f32 v[8:9], v[12:13], v[8:9]
	v_pk_mul_f32 v[12:13], v[6:7], s[48:49] op_sel_hi:[1,0]
	v_pk_mul_f32 v[10:11], v[14:15], v[10:11]
	v_pk_mul_f32 v[14:15], v[4:5], s[48:49] op_sel_hi:[1,0]
	v_exp_f32_e32 v12, v12
	v_exp_f32_e32 v14, v14
	v_exp_f32_e32 v15, v15
	v_exp_f32_e32 v13, v13
	v_mad_i64_i32 v[16:17], s[26:27], v16, s90, v[138:139]
	v_pk_add_f32 v[14:15], v[14:15], 1.0 op_sel_hi:[1,0]
	v_pk_add_f32 v[12:13], v[12:13], 1.0 op_sel_hi:[1,0]
	v_rcp_f32_e32 v4, v14
	v_rcp_f32_e32 v5, v15
	v_rcp_f32_e32 v6, v12
	v_rcp_f32_e32 v7, v13
	v_lshl_add_u64 v[16:17], v[16:17], 0, v[140:141]
	s_and_b64 vcc, exec, s[4:5]
	s_mov_b32 s57, s56
	v_pk_mul_f32 v[6:7], v[6:7], v[2:3]
	v_pk_mul_f32 v[2:3], v[4:5], v[0:1]
	s_mov_b32 s66, s20
	s_mov_b64 s[28:29], s[8:9]
	s_mov_b64 s[26:27], s[6:7]
	v_cvt_pk_bf16_f32 v0, v8, v9
	v_cvt_pk_bf16_f32 v1, v10, v11
	v_cvt_pk_bf16_f32 v2, v2, v3
	v_cvt_pk_bf16_f32 v3, v6, v7
	global_store_dwordx4 v[16:17], v[0:3], off
	s_cbranch_vccz .LBB0_693
	s_waitcnt vmcnt(0)
	s_cmpk_gt_u32 s18, 0xff
	s_mov_b32 s55, 0xbc00000
	s_cbranch_scc1 .LBB0_704
	s_barrier

.LBB0_773:
	s_add_i32 s83, s28, 2
	s_add_u32 s30, s16, 0x80
	s_addc_u32 s29, s17, 0
	s_add_i32 s88, 0, 0x10000
	v_add_u32_e32 v138, s88, v141
	ds_read_b128 v[162:165], v138
	ds_read_b128 v[170:173], v138 offset:2048
	ds_read_b128 v[166:169], v138 offset:1024
	ds_read_b128 v[174:177], v138 offset:3072
	s_cmp_eq_u32 s67, s28
	s_cselect_b32 s28, s6, s30
	s_cselect_b32 s29, s7, s29
	s_cselect_b32 s31, s9, s82
	s_cselect_b32 s30, s8, s75
	v_lshl_add_u64 v[138:139], s[16:17], 0, v[134:135]
	s_add_i32 m0, s37, 0xc000
	ds_read_b128 v[178:181], v143
	ds_read_b128 v[198:201], v143 offset:2048
	ds_read_b128 v[206:209], v143 offset:4096
	ds_read_b128 v[214:217], v143 offset:6144
	ds_read_b128 v[194:197], v143 offset:1024
	ds_read_b128 v[202:205], v143 offset:3072
	ds_read_b128 v[210:213], v143 offset:5120
	ds_read_b128 v[218:221], v143 offset:7168
	global_load_lds_dwordx4 v[138:139], off
	v_lshl_add_u64 v[138:139], s[16:17], 0, v[136:137]
	s_add_i32 m0, s37, 0xe000
	s_nop 0
	global_load_lds_dwordx4 v[138:139], off
	s_barrier
	s_setprio 1
	s_waitcnt lgkmcnt(7)
	v_mfma_f32_16x16x32_bf16 v[124:127], v[162:165], v[178:181], v[124:127]
	v_mfma_f32_16x16x32_bf16 v[120:123], v[170:173], v[178:181], v[120:123]
	s_waitcnt lgkmcnt(6)
	v_mfma_f32_16x16x32_bf16 v[116:119], v[162:165], v[198:201], v[116:119]
	v_mfma_f32_16x16x32_bf16 v[108:111], v[170:173], v[198:201], v[108:111]
	s_waitcnt lgkmcnt(5)
	v_mfma_f32_16x16x32_bf16 v[100:103], v[162:165], v[206:209], v[100:103]
	v_mfma_f32_16x16x32_bf16 v[92:95], v[170:173], v[206:209], v[92:95]
	s_waitcnt lgkmcnt(4)
	v_mfma_f32_16x16x32_bf16 v[84:87], v[162:165], v[214:217], v[84:87]
	v_mfma_f32_16x16x32_bf16 v[76:79], v[170:173], v[214:217], v[76:79]
	s_waitcnt lgkmcnt(3)
	v_mfma_f32_16x16x32_bf16 v[124:127], v[166:169], v[194:197], v[124:127]
	v_mfma_f32_16x16x32_bf16 v[120:123], v[174:177], v[194:197], v[120:123]
	s_waitcnt lgkmcnt(2)
	v_mfma_f32_16x16x32_bf16 v[116:119], v[166:169], v[202:205], v[116:119]
	v_mfma_f32_16x16x32_bf16 v[108:111], v[174:177], v[202:205], v[108:111]
	s_waitcnt lgkmcnt(1)
	v_mfma_f32_16x16x32_bf16 v[100:103], v[166:169], v[210:213], v[100:103]
	v_mfma_f32_16x16x32_bf16 v[92:95], v[174:177], v[210:213], v[92:95]
	s_waitcnt lgkmcnt(0)
	v_mfma_f32_16x16x32_bf16 v[84:87], v[166:169], v[218:221], v[84:87]
	v_mfma_f32_16x16x32_bf16 v[76:79], v[174:177], v[218:221], v[76:79]
	s_setprio 0
	s_barrier
	s_add_i32 s89, 0, 0x14000
	v_add_u32_e32 v138, s89, v141
	s_add_i32 s88, s88, s36
	ds_read_b128 v[222:225], v138
	ds_read_b128 v[230:233], v138 offset:2048
	ds_read_b128 v[226:229], v138 offset:1024
	ds_read_b128 v[234:237], v138 offset:3072
	v_lshl_add_u64 v[138:139], s[30:31], 0, v[144:145]
	s_mov_b32 m0, s88
	v_lshl_add_u64 v[238:239], s[30:31], 0, v[128:129]
	global_load_lds_dwordx4 v[138:139], off
	s_add_i32 m0, s88, 0x2000
	s_nop 0
	global_load_lds_dwordx4 v[238:239], off
	s_barrier
	s_setprio 1
	s_waitcnt lgkmcnt(3)
	v_mfma_f32_16x16x32_bf16 v[112:115], v[222:225], v[178:181], v[112:115]
	s_waitcnt lgkmcnt(2)
	v_mfma_f32_16x16x32_bf16 v[104:107], v[230:233], v[178:181], v[104:107]
	v_mfma_f32_16x16x32_bf16 v[96:99], v[222:225], v[198:201], v[96:99]
	v_mfma_f32_16x16x32_bf16 v[88:91], v[230:233], v[198:201], v[88:91]
	v_mfma_f32_16x16x32_bf16 v[80:83], v[222:225], v[206:209], v[80:83]
	v_mfma_f32_16x16x32_bf16 v[72:75], v[230:233], v[206:209], v[72:75]
	v_mfma_f32_16x16x32_bf16 v[68:71], v[222:225], v[214:217], v[68:71]
	v_mfma_f32_16x16x32_bf16 v[64:67], v[230:233], v[214:217], v[64:67]
	s_waitcnt lgkmcnt(1)
	v_mfma_f32_16x16x32_bf16 v[112:115], v[226:229], v[194:197], v[112:115]
	s_waitcnt lgkmcnt(0)
	v_mfma_f32_16x16x32_bf16 v[104:107], v[234:237], v[194:197], v[104:107]
	v_mfma_f32_16x16x32_bf16 v[96:99], v[226:229], v[202:205], v[96:99]
	v_mfma_f32_16x16x32_bf16 v[88:91], v[234:237], v[202:205], v[88:91]
	v_mfma_f32_16x16x32_bf16 v[80:83], v[226:229], v[210:213], v[80:83]
	v_mfma_f32_16x16x32_bf16 v[72:75], v[234:237], v[210:213], v[72:75]
	v_mfma_f32_16x16x32_bf16 v[68:71], v[226:229], v[218:221], v[68:71]
	v_mfma_f32_16x16x32_bf16 v[64:67], v[234:237], v[218:221], v[64:67]
	s_setprio 0
	s_mov_b32 m0, s37
	v_lshl_add_u64 v[240:241], s[28:29], 0, v[132:133]
	s_barrier
	ds_read_b128 v[178:181], v143 offset:16384
	ds_read_b128 v[198:201], v143 offset:18432
	ds_read_b128 v[206:209], v143 offset:20480
	ds_read_b128 v[214:217], v143 offset:22528
	ds_read_b128 v[194:197], v143 offset:17408
	ds_read_b128 v[202:205], v143 offset:19456
	ds_read_b128 v[210:213], v143 offset:21504
	ds_read_b128 v[218:221], v143 offset:23552
	global_load_lds_dwordx4 v[240:241], off
	v_lshl_add_u64 v[242:243], s[28:29], 0, v[130:131]
	s_mov_b32 m0, s50
	s_nop 0
	global_load_lds_dwordx4 v[242:243], off
	s_barrier
	s_setprio 1
	s_waitcnt lgkmcnt(7)
	v_mfma_f32_16x16x32_bf16 v[60:63], v[162:165], v[178:181], v[60:63]
	v_mfma_f32_16x16x32_bf16 v[56:59], v[170:173], v[178:181], v[56:59]
	s_waitcnt lgkmcnt(6)
	v_mfma_f32_16x16x32_bf16 v[52:55], v[162:165], v[198:201], v[52:55]
	v_mfma_f32_16x16x32_bf16 v[48:51], v[170:173], v[198:201], v[48:51]
	s_waitcnt lgkmcnt(5)
	v_mfma_f32_16x16x32_bf16 v[36:39], v[162:165], v[206:209], v[36:39]
	v_mfma_f32_16x16x32_bf16 v[32:35], v[170:173], v[206:209], v[32:35]
	s_waitcnt lgkmcnt(4)
	v_mfma_f32_16x16x32_bf16 v[20:23], v[162:165], v[214:217], v[20:23]
	v_mfma_f32_16x16x32_bf16 v[16:19], v[170:173], v[214:217], v[16:19]
	s_waitcnt lgkmcnt(3)
	v_mfma_f32_16x16x32_bf16 v[60:63], v[166:169], v[194:197], v[60:63]
	v_mfma_f32_16x16x32_bf16 v[56:59], v[174:177], v[194:197], v[56:59]
	s_waitcnt lgkmcnt(2)
	v_mfma_f32_16x16x32_bf16 v[52:55], v[166:169], v[202:205], v[52:55]
	v_mfma_f32_16x16x32_bf16 v[48:51], v[174:177], v[202:205], v[48:51]
	s_waitcnt lgkmcnt(1)
	v_mfma_f32_16x16x32_bf16 v[36:39], v[166:169], v[210:213], v[36:39]
	v_mfma_f32_16x16x32_bf16 v[32:35], v[174:177], v[210:213], v[32:35]
	s_waitcnt lgkmcnt(0)
	v_mfma_f32_16x16x32_bf16 v[20:23], v[166:169], v[218:221], v[20:23]
	v_mfma_f32_16x16x32_bf16 v[16:19], v[174:177], v[218:221], v[16:19]
	s_setprio 0
	s_barrier
	s_add_u32 s30, s30, s76
	s_addc_u32 s31, s31, 0
	s_add_i32 s88, s89, s36
	v_lshl_add_u64 v[244:245], s[30:31], 0, v[144:145]
	s_mov_b32 m0, s88
	v_lshl_add_u64 v[246:247], s[30:31], 0, v[128:129]
	global_load_lds_dwordx4 v[244:245], off
	s_add_i32 m0, s88, 0x2000
	s_nop 0
	global_load_lds_dwordx4 v[246:247], off
	s_waitcnt vmcnt(6)
	s_barrier
	s_setprio 1
	v_mfma_f32_16x16x32_bf16 v[44:47], v[222:225], v[178:181], v[44:47]
	v_mfma_f32_16x16x32_bf16 v[40:43], v[230:233], v[178:181], v[40:43]
	v_mfma_f32_16x16x32_bf16 v[28:31], v[222:225], v[198:201], v[28:31]
	v_mfma_f32_16x16x32_bf16 v[24:27], v[230:233], v[198:201], v[24:27]
	v_mfma_f32_16x16x32_bf16 v[12:15], v[222:225], v[206:209], v[12:15]
	v_mfma_f32_16x16x32_bf16 v[8:11], v[230:233], v[206:209], v[8:11]
	v_mfma_f32_16x16x32_bf16 v[4:7], v[222:225], v[214:217], v[4:7]
	v_mfma_f32_16x16x32_bf16 v[0:3], v[230:233], v[214:217], v[0:3]
	v_mfma_f32_16x16x32_bf16 v[44:47], v[226:229], v[194:197], v[44:47]
	v_mfma_f32_16x16x32_bf16 v[40:43], v[234:237], v[194:197], v[40:43]
	v_mfma_f32_16x16x32_bf16 v[28:31], v[226:229], v[202:205], v[28:31]
	v_mfma_f32_16x16x32_bf16 v[24:27], v[234:237], v[202:205], v[24:27]
	v_mfma_f32_16x16x32_bf16 v[12:15], v[226:229], v[210:213], v[12:15]
	v_mfma_f32_16x16x32_bf16 v[8:11], v[234:237], v[210:213], v[8:11]
	v_mfma_f32_16x16x32_bf16 v[4:7], v[226:229], v[218:221], v[4:7]
	v_mfma_f32_16x16x32_bf16 v[0:3], v[234:237], v[218:221], v[0:3]
	s_setprio 0
	s_add_i32 s30, 0, 0x18000
	v_add_u32_e32 v174, s30, v141
	s_barrier
	ds_read_b128 v[162:165], v174
	ds_read_b128 v[170:173], v174 offset:2048
	ds_read_b128 v[166:169], v174 offset:1024
	ds_read_b128 v[174:177], v174 offset:3072
	s_add_u32 s28, s28, s76
	s_addc_u32 s29, s29, 0
	s_mov_b32 m0, s51
	v_lshl_add_u64 v[222:223], s[28:29], 0, v[132:133]
	ds_read_b128 v[178:181], v143 offset:32768
	ds_read_b128 v[198:201], v143 offset:34816
	ds_read_b128 v[206:209], v143 offset:36864
	ds_read_b128 v[214:217], v143 offset:38912
	ds_read_b128 v[194:197], v143 offset:33792
	ds_read_b128 v[202:205], v143 offset:35840
	ds_read_b128 v[210:213], v143 offset:37888
	ds_read_b128 v[218:221], v143 offset:39936
	global_load_lds_dwordx4 v[222:223], off
	v_lshl_add_u64 v[222:223], s[28:29], 0, v[130:131]
	s_mov_b32 m0, s54
	s_nop 0
	global_load_lds_dwordx4 v[222:223], off
	s_barrier
	s_setprio 1
	s_waitcnt lgkmcnt(7)
	v_mfma_f32_16x16x32_bf16 v[124:127], v[162:165], v[178:181], v[124:127]
	v_mfma_f32_16x16x32_bf16 v[120:123], v[170:173], v[178:181], v[120:123]
	s_waitcnt lgkmcnt(6)
	v_mfma_f32_16x16x32_bf16 v[116:119], v[162:165], v[198:201], v[116:119]
	v_mfma_f32_16x16x32_bf16 v[108:111], v[170:173], v[198:201], v[108:111]
	s_waitcnt lgkmcnt(5)
	v_mfma_f32_16x16x32_bf16 v[100:103], v[162:165], v[206:209], v[100:103]
	v_mfma_f32_16x16x32_bf16 v[92:95], v[170:173], v[206:209], v[92:95]
	s_waitcnt lgkmcnt(4)
	v_mfma_f32_16x16x32_bf16 v[84:87], v[162:165], v[214:217], v[84:87]
	v_mfma_f32_16x16x32_bf16 v[76:79], v[170:173], v[214:217], v[76:79]
	s_waitcnt lgkmcnt(3)
	v_mfma_f32_16x16x32_bf16 v[124:127], v[166:169], v[194:197], v[124:127]
	v_mfma_f32_16x16x32_bf16 v[120:123], v[174:177], v[194:197], v[120:123]
	s_waitcnt lgkmcnt(2)
	v_mfma_f32_16x16x32_bf16 v[116:119], v[166:169], v[202:205], v[116:119]
	v_mfma_f32_16x16x32_bf16 v[108:111], v[174:177], v[202:205], v[108:111]
	s_waitcnt lgkmcnt(1)
	v_mfma_f32_16x16x32_bf16 v[100:103], v[166:169], v[210:213], v[100:103]
	v_mfma_f32_16x16x32_bf16 v[92:95], v[174:177], v[210:213], v[92:95]
	s_waitcnt lgkmcnt(0)
	v_mfma_f32_16x16x32_bf16 v[84:87], v[166:169], v[218:221], v[84:87]
	v_mfma_f32_16x16x32_bf16 v[76:79], v[174:177], v[218:221], v[76:79]
	s_setprio 0
	s_barrier
	s_add_i32 s28, 0, 0x1c000
	s_add_i32 s29, s30, s36
	v_add_u32_e32 v193, s28, v141
	v_lshl_add_u64 v[138:139], v[138:139], 0, s[86:87]
	s_mov_b32 m0, s29
	ds_read_b128 v[222:225], v193
	ds_read_b128 v[230:233], v193 offset:2048
	ds_read_b128 v[226:229], v193 offset:1024
	ds_read_b128 v[234:237], v193 offset:3072
	global_load_lds_dwordx4 v[138:139], off
	v_lshl_add_u64 v[138:139], v[238:239], 0, s[86:87]
	s_add_i32 m0, s29, 0x2000
	s_nop 0
	global_load_lds_dwordx4 v[138:139], off
	s_barrier
	s_setprio 1
	s_waitcnt lgkmcnt(3)
	v_mfma_f32_16x16x32_bf16 v[112:115], v[222:225], v[178:181], v[112:115]
	s_waitcnt lgkmcnt(2)
	v_mfma_f32_16x16x32_bf16 v[104:107], v[230:233], v[178:181], v[104:107]
	v_mfma_f32_16x16x32_bf16 v[96:99], v[222:225], v[198:201], v[96:99]
	v_mfma_f32_16x16x32_bf16 v[88:91], v[230:233], v[198:201], v[88:91]
	v_mfma_f32_16x16x32_bf16 v[80:83], v[222:225], v[206:209], v[80:83]
	v_mfma_f32_16x16x32_bf16 v[72:75], v[230:233], v[206:209], v[72:75]
	v_mfma_f32_16x16x32_bf16 v[68:71], v[222:225], v[214:217], v[68:71]
	v_mfma_f32_16x16x32_bf16 v[64:67], v[230:233], v[214:217], v[64:67]
	s_waitcnt lgkmcnt(1)
	v_mfma_f32_16x16x32_bf16 v[112:115], v[226:229], v[194:197], v[112:115]
	s_waitcnt lgkmcnt(0)
	v_mfma_f32_16x16x32_bf16 v[104:107], v[234:237], v[194:197], v[104:107]
	v_mfma_f32_16x16x32_bf16 v[96:99], v[226:229], v[202:205], v[96:99]
	v_mfma_f32_16x16x32_bf16 v[88:91], v[234:237], v[202:205], v[88:91]
	v_mfma_f32_16x16x32_bf16 v[80:83], v[226:229], v[210:213], v[80:83]
	v_mfma_f32_16x16x32_bf16 v[72:75], v[234:237], v[210:213], v[72:75]
	v_mfma_f32_16x16x32_bf16 v[68:71], v[226:229], v[218:221], v[68:71]
	v_mfma_f32_16x16x32_bf16 v[64:67], v[234:237], v[218:221], v[64:67]
	s_setprio 0
	s_mov_b32 m0, s57
	v_lshl_add_u64 v[138:139], v[240:241], 0, s[86:87]
	s_barrier
	ds_read_b128 v[178:181], v143 offset:49152
	ds_read_b128 v[198:201], v143 offset:51200
	ds_read_b128 v[206:209], v143 offset:53248
	ds_read_b128 v[214:217], v143 offset:55296
	ds_read_b128 v[194:197], v143 offset:50176
	ds_read_b128 v[202:205], v143 offset:52224
	ds_read_b128 v[210:213], v143 offset:54272
	ds_read_b128 v[218:221], v143 offset:56320
	global_load_lds_dwordx4 v[138:139], off
	v_lshl_add_u64 v[138:139], v[242:243], 0, s[86:87]
	s_mov_b32 m0, s66
	s_nop 0
	global_load_lds_dwordx4 v[138:139], off
	s_barrier
	s_setprio 1
	s_waitcnt lgkmcnt(7)
	v_mfma_f32_16x16x32_bf16 v[60:63], v[162:165], v[178:181], v[60:63]
	v_mfma_f32_16x16x32_bf16 v[56:59], v[170:173], v[178:181], v[56:59]
	s_waitcnt lgkmcnt(6)
	v_mfma_f32_16x16x32_bf16 v[52:55], v[162:165], v[198:201], v[52:55]
	v_mfma_f32_16x16x32_bf16 v[48:51], v[170:173], v[198:201], v[48:51]
	s_waitcnt lgkmcnt(5)
	v_mfma_f32_16x16x32_bf16 v[36:39], v[162:165], v[206:209], v[36:39]
	v_mfma_f32_16x16x32_bf16 v[32:35], v[170:173], v[206:209], v[32:35]
	s_waitcnt lgkmcnt(4)
	v_mfma_f32_16x16x32_bf16 v[20:23], v[162:165], v[214:217], v[20:23]
	v_mfma_f32_16x16x32_bf16 v[16:19], v[170:173], v[214:217], v[16:19]
	s_waitcnt lgkmcnt(3)
	v_mfma_f32_16x16x32_bf16 v[60:63], v[166:169], v[194:197], v[60:63]
	v_mfma_f32_16x16x32_bf16 v[56:59], v[174:177], v[194:197], v[56:59]
	s_waitcnt lgkmcnt(2)
	v_mfma_f32_16x16x32_bf16 v[52:55], v[166:169], v[202:205], v[52:55]
	v_mfma_f32_16x16x32_bf16 v[48:51], v[174:177], v[202:205], v[48:51]
	s_waitcnt lgkmcnt(1)
	v_mfma_f32_16x16x32_bf16 v[36:39], v[166:169], v[210:213], v[36:39]
	v_mfma_f32_16x16x32_bf16 v[32:35], v[174:177], v[210:213], v[32:35]
	s_waitcnt lgkmcnt(0)
	v_mfma_f32_16x16x32_bf16 v[20:23], v[166:169], v[218:221], v[20:23]
	v_mfma_f32_16x16x32_bf16 v[16:19], v[174:177], v[218:221], v[16:19]
	s_setprio 0
	s_barrier
	s_add_i32 s28, s28, s36
	v_lshl_add_u64 v[138:139], v[244:245], 0, s[86:87]
	s_mov_b32 m0, s28
	s_nop 0
	global_load_lds_dwordx4 v[138:139], off
	v_lshl_add_u64 v[138:139], v[246:247], 0, s[86:87]
	s_add_i32 m0, s28, 0x2000
	s_nop 0
	global_load_lds_dwordx4 v[138:139], off
	s_waitcnt vmcnt(6)
	s_barrier
	s_setprio 1
	v_mfma_f32_16x16x32_bf16 v[44:47], v[222:225], v[178:181], v[44:47]
	v_mfma_f32_16x16x32_bf16 v[40:43], v[230:233], v[178:181], v[40:43]
	v_mfma_f32_16x16x32_bf16 v[28:31], v[222:225], v[198:201], v[28:31]
	v_mfma_f32_16x16x32_bf16 v[24:27], v[230:233], v[198:201], v[24:27]
	v_mfma_f32_16x16x32_bf16 v[12:15], v[222:225], v[206:209], v[12:15]
	v_mfma_f32_16x16x32_bf16 v[8:11], v[230:233], v[206:209], v[8:11]
	v_mfma_f32_16x16x32_bf16 v[4:7], v[222:225], v[214:217], v[4:7]
	v_mfma_f32_16x16x32_bf16 v[0:3], v[230:233], v[214:217], v[0:3]
	v_mfma_f32_16x16x32_bf16 v[44:47], v[226:229], v[194:197], v[44:47]
	v_mfma_f32_16x16x32_bf16 v[40:43], v[234:237], v[194:197], v[40:43]
	v_mfma_f32_16x16x32_bf16 v[28:31], v[226:229], v[202:205], v[28:31]
	v_mfma_f32_16x16x32_bf16 v[24:27], v[234:237], v[202:205], v[24:27]
	v_mfma_f32_16x16x32_bf16 v[12:15], v[226:229], v[210:213], v[12:15]
	v_mfma_f32_16x16x32_bf16 v[8:11], v[234:237], v[210:213], v[8:11]
	v_mfma_f32_16x16x32_bf16 v[4:7], v[226:229], v[218:221], v[4:7]
	v_mfma_f32_16x16x32_bf16 v[0:3], v[234:237], v[218:221], v[0:3]
	s_setprio 0
	s_add_u32 s16, s16, 0x100
	s_addc_u32 s17, s17, 0
	s_add_u32 s75, s75, 0x100
	s_addc_u32 s82, s82, 0
	s_cmp_ge_u32 s83, s56
	s_mov_b32 s28, s83
	s_barrier
	s_cbranch_scc0 .LBB0_773
	s_ashr_i32 s16, s73, 31
	s_lshr_b32 s16, s16, 29
	s_add_i32 s16, s73, s16
	s_and_b32 s16, s16, 0xfffff8
	s_sub_i32 s16, s73, s16
	v_lshl_add_u32 v162, s74, 8, v140
	v_lshl_or_b32 v138, s16, 8, v142
	v_ashrrev_i32_e32 v139, 31, v138
	v_ashrrev_i32_e32 v163, 31, v162
	v_lshl_add_u64 v[164:165], v[138:139], 1, s[10:11]
	v_lshlrev_b64 v[138:139], 12, v[162:163]
	v_lshl_add_u64 v[138:139], v[164:165], 0, v[138:139]
	v_cvt_pk_bf16_f32 v60, v60, v61
	v_cvt_pk_bf16_f32 v61, v62, v63
	v_cvt_pk_bf16_f32 v62, v56, v57
	v_add_co_u32_e32 v56, vcc, s3, v138
	v_cvt_pk_bf16_f32 v68, v68, v69
	v_cvt_pk_bf16_f32 v69, v70, v71
	v_cvt_pk_bf16_f32 v70, v64, v65
	v_lshl_add_u64 v[64:65], v[138:139], 0, s[84:85]
	s_nop 0
	v_addc_co_u32_e32 v57, vcc, 0, v139, vcc
	v_cvt_pk_bf16_f32 v44, v44, v45
	v_cvt_pk_bf16_f32 v45, v46, v47
	v_cvt_pk_bf16_f32 v46, v40, v41
	v_cvt_pk_bf16_f32 v47, v42, v43
	global_store_dwordx4 v[64:65], v[44:47], off offset:256
	v_cvt_pk_bf16_f32 v112, v112, v113
	v_cvt_pk_bf16_f32 v113, v114, v115
	v_cvt_pk_bf16_f32 v114, v104, v105
	v_or_b32_e32 v104, 16, v162
	v_cvt_pk_bf16_f32 v28, v28, v29
	s_nop 0
	v_add_co_u32_e32 v46, vcc, s93, v138
	v_lshl_add_u64 v[44:45], v[138:139], 0, s[46:47]
	s_nop 0
	v_addc_co_u32_e32 v47, vcc, 0, v139, vcc
	v_cvt_pk_bf16_f32 v29, v30, v31
	v_cvt_pk_bf16_f32 v30, v24, v25
	v_ashrrev_i32_e32 v105, 31, v104
	v_cvt_pk_bf16_f32 v96, v96, v97
	v_cvt_pk_bf16_f32 v97, v98, v99
	v_cvt_pk_bf16_f32 v98, v88, v89
	v_or_b32_e32 v88, 32, v162
	v_cvt_pk_bf16_f32 v31, v26, v27
	global_store_dwordx4 v[44:45], v[28:31], off offset:256
	v_lshlrev_b64 v[104:105], 12, v[104:105]
	v_ashrrev_i32_e32 v89, 31, v88
	v_add_co_u32_e32 v30, vcc, s97, v138
	v_cvt_pk_bf16_f32 v80, v80, v81
	v_cvt_pk_bf16_f32 v81, v82, v83
	v_cvt_pk_bf16_f32 v82, v72, v73
	v_or_b32_e32 v72, 48, v162
	v_lshl_add_u64 v[28:29], v[138:139], 0, s[42:43]
	v_addc_co_u32_e32 v31, vcc, 0, v139, vcc
	v_cvt_pk_bf16_f32 v12, v12, v13
	v_cvt_pk_bf16_f32 v13, v14, v15
	v_cvt_pk_bf16_f32 v14, v8, v9
	v_cvt_pk_bf16_f32 v115, v106, v107
	global_store_dwordx4 v[138:139], v[112:115], off offset:256
	v_lshlrev_b64 v[88:89], 12, v[88:89]
	v_ashrrev_i32_e32 v73, 31, v72
	v_lshl_add_u64 v[112:113], v[164:165], 0, v[104:105]
	v_cvt_pk_bf16_f32 v15, v10, v11
	global_store_dwordx4 v[28:29], v[12:15], off offset:256
	v_cvt_pk_bf16_f32 v99, v90, v91
	global_store_dwordx4 v[112:113], v[96:99], off offset:256
	v_lshlrev_b64 v[72:73], 12, v[72:73]
	v_add_co_u32_e32 v14, vcc, s91, v138
	v_lshl_add_u64 v[96:97], v[164:165], 0, v[88:89]
	s_nop 0
	v_addc_co_u32_e32 v15, vcc, 0, v139, vcc
	v_cvt_pk_bf16_f32 v83, v74, v75
	global_store_dwordx4 v[96:97], v[80:83], off offset:256
	v_lshl_add_u64 v[12:13], v[138:139], 0, s[62:63]
	s_and_b64 vcc, exec, s[4:5]
	v_lshl_add_u64 v[80:81], v[164:165], 0, v[72:73]
	s_mov_b32 s73, s71
	s_mov_b32 s74, s72
	s_mov_b64 s[28:29], s[8:9]
	s_mov_b64 s[16:17], s[6:7]
	v_cvt_pk_bf16_f32 v124, v124, v125
	v_cvt_pk_bf16_f32 v125, v126, v127
	v_cvt_pk_bf16_f32 v126, v120, v121
	v_cvt_pk_bf16_f32 v127, v122, v123
	global_store_dwordx4 v[138:139], v[124:127], off
	v_cvt_pk_bf16_f32 v104, v116, v117
	v_cvt_pk_bf16_f32 v105, v118, v119
	v_cvt_pk_bf16_f32 v106, v108, v109
	v_cvt_pk_bf16_f32 v107, v110, v111
	global_store_dwordx4 v[112:113], v[104:107], off
	v_cvt_pk_bf16_f32 v88, v100, v101
	v_cvt_pk_bf16_f32 v89, v102, v103
	v_cvt_pk_bf16_f32 v90, v92, v93
	v_cvt_pk_bf16_f32 v91, v94, v95
	global_store_dwordx4 v[96:97], v[88:91], off
	v_cvt_pk_bf16_f32 v72, v84, v85
	v_cvt_pk_bf16_f32 v73, v86, v87
	v_cvt_pk_bf16_f32 v74, v76, v77
	v_cvt_pk_bf16_f32 v75, v78, v79
	global_store_dwordx4 v[80:81], v[72:75], off
	v_cvt_pk_bf16_f32 v71, v66, v67
	global_store_dwordx4 v[80:81], v[68:71], off offset:256
	v_cvt_pk_bf16_f32 v63, v58, v59
	global_store_dwordx4 v[56:57], v[60:63], off
	v_cvt_pk_bf16_f32 v40, v52, v53
	v_cvt_pk_bf16_f32 v41, v54, v55
	v_cvt_pk_bf16_f32 v42, v48, v49
	v_cvt_pk_bf16_f32 v43, v50, v51
	global_store_dwordx4 v[46:47], v[40:43], off
	v_cvt_pk_bf16_f32 v24, v36, v37
	v_cvt_pk_bf16_f32 v25, v38, v39
	v_cvt_pk_bf16_f32 v26, v32, v33
	v_cvt_pk_bf16_f32 v27, v34, v35
	global_store_dwordx4 v[30:31], v[24:27], off
	v_cvt_pk_bf16_f32 v8, v20, v21
	v_cvt_pk_bf16_f32 v9, v22, v23
	v_cvt_pk_bf16_f32 v10, v16, v17
	v_cvt_pk_bf16_f32 v11, v18, v19
	global_store_dwordx4 v[14:15], v[8:11], off
	v_cvt_pk_bf16_f32 v4, v4, v5
	v_cvt_pk_bf16_f32 v5, v6, v7
	v_cvt_pk_bf16_f32 v6, v0, v1
	v_cvt_pk_bf16_f32 v7, v2, v3
	global_store_dwordx4 v[12:13], v[4:7], off offset:256
	s_cbranch_vccz .LBB0_762
	s_waitcnt vmcnt(0)
	s_cmpk_gt_u32 s13, 0xff
	s_mov_b32 s55, 0xbc00000
	s_cbranch_scc1 .LBB0_777
	s_barrier
